# K-loops: per-segment s_setprio toggling removed, one static priority raise for the trailing wave half per stage
# speedup vs baseline: 1.0007x; 1.0007x over previous
.LBB0_357:
	v_readlane_b32 s0, v246, 2
	v_readlane_b32 s1, v246, 3
	s_add_u32 s4, s0, 0x2400000
	s_addc_u32 s5, s1, 0
	s_waitcnt vmcnt(1)
	v_lshrrev_b32_e32 v3, 1, v0
	v_lshrrev_b32_e32 v4, 5, v0
	s_add_u32 s15, s0, 0x100000
	v_lshlrev_b32_e32 v1, 4, v0
	v_and_b32_e32 v2, 32, v0
	v_and_b32_e32 v3, 24, v3
	v_and_b32_e32 v4, 4, v4
	v_bfe_u32 v5, v0, 2, 2
	s_addc_u32 s78, s1, 0
	v_bfe_u32 v12, v0, 2, 4
	v_bitop3_b32 v10, v1, v2, 48 bitop3:0x6c
	v_and_b32_e32 v11, 64, v0
	v_or3_b32 v3, v4, v5, v3
	v_lshrrev_b32_e32 v4, 3, v0
	v_or_b32_e32 v13, 0x2000, v1
	s_lshl_b32 s8, s63, 4
	s_and_b32 s3, s86, 7
	v_readfirstlane_b32 s0, v0
	v_or_b32_e32 v2, v10, v11
	v_and_or_b32 v5, v4, 48, v12
	v_and_or_b32 v4, v4, 32, v3
	v_lshrrev_b32_e32 v1, 7, v13
	s_movk_i32 s2, 0x70
	s_mov_b32 s6, s8
	s_or_b32 s30, s8, s3
	s_lshr_b32 s1, s0, 6
	v_lshl_or_b32 v164, v4, 11, v2
	v_and_or_b32 v4, v1, s2, v12
	s_movk_i32 s2, 0x60
	v_writelane_b32 v246, s6, 17
	s_lshr_b32 s72, s77, 3
	s_ashr_i32 s31, s30, 31
	v_and_or_b32 v1, v1, s2, v3
	s_lshr_b32 s2, s0, 8
	s_lshl_b32 s79, s1, 10
	v_writelane_b32 v246, s7, 18
	s_lshl_b64 s[6:7], s[30:31], 19
	s_lshl_b32 s3, s72, 19
	s_add_u32 s8, s15, s3
	s_addc_u32 s9, s78, 0
	s_add_i32 s31, s79, 0
	s_add_i32 m0, s31, 0x10000
	s_barrier
	global_load_lds_dwordx4 v164, s[8:9]
	s_add_i32 m0, s31, 0x12000
	v_lshl_or_b32 v168, v1, 11, v2
	s_add_u32 s10, s8, 0x40000
	global_load_lds_dwordx4 v168, s[8:9]
	s_addc_u32 s11, s9, 0
	s_add_i32 m0, s31, 0x14000
	v_lshl_or_b32 v162, v5, 11, v2
	global_load_lds_dwordx4 v164, s[10:11]
	s_add_i32 m0, s31, 0x16000
	s_add_u32 s6, s4, s6
	s_addc_u32 s7, s5, s7
	s_add_i32 s80, s31, 0x2000
	global_load_lds_dwordx4 v168, s[10:11]
	s_mov_b32 m0, s31
	s_add_u32 s10, s6, 0x40000
	v_lshl_or_b32 v166, v4, 11, v2
	global_load_lds_dwordx4 v162, s[6:7]
	s_mov_b32 m0, s80
	s_addc_u32 s11, s7, 0
	s_add_i32 s81, s31, 0x4000
	global_load_lds_dwordx4 v166, s[6:7]
	s_mov_b32 m0, s81
	s_add_i32 s82, s31, 0x6000
	global_load_lds_dwordx4 v162, s[10:11]
	s_mov_b32 m0, s82
	v_mov_b32_e32 v171, 0
	global_load_lds_dwordx4 v166, s[10:11]
	v_mov_b32_e32 v165, v171
	v_mov_b32_e32 v169, v171
	v_mov_b32_e32 v163, v171
	v_mov_b32_e32 v167, v171
	s_cmp_eq_u32 s2, 1
	v_lshl_add_u64 v[8:9], s[8:9], 0, v[164:165]
	v_lshl_add_u64 v[4:5], s[8:9], 0, v[168:169]
	v_lshl_add_u64 v[2:3], s[6:7], 0, v[162:163]
	s_cselect_b64 s[34:35], -1, 0
	s_cmp_lg_u32 s2, 1
	v_lshl_add_u64 v[6:7], s[6:7], 0, v[166:167]
	s_cbranch_scc1 .LBB0_359
	s_barrier
	s_setprio 1

.LBB0_368:
	ds_read_b128 v[114:117], v197
	ds_read_b128 v[134:137], v197 offset:1024
	ds_read_b128 v[138:141], v197 offset:2048
	ds_read_b128 v[142:145], v197 offset:3072
	ds_read_b128 v[146:149], v198
	ds_read_b128 v[150:153], v198 offset:1024
	ds_read_b128 v[154:157], v198 offset:2048
	ds_read_b128 v[158:161], v198 offset:3072
	s_add_u32 s0, s6, 0xfffc0080
	s_addc_u32 s8, s7, -1
	s_cmp_eq_u32 s26, 12
	s_cselect_b32 s11, s2, s8
	s_cselect_b32 s10, s3, s0
	s_cselect_b32 s9, s12, s25
	s_cselect_b32 s8, s13, s24
	s_add_i32 m0, s31, 0xc000
	ds_read_b128 v[184:187], v199
	ds_read_b128 v[188:191], v199 offset:1024
	ds_read_b128 v[206:209], v199 offset:2048
	ds_read_b128 v[210:213], v199 offset:3072
	ds_read_b128 v[214:217], v199 offset:4096
	ds_read_b128 v[218:221], v199 offset:5120
	ds_read_b128 v[222:225], v199 offset:6144
	ds_read_b128 v[226:229], v199 offset:7168
	global_load_lds_dwordx4 v180, s[6:7]
	s_add_i32 m0, s31, 0xe000
	s_nop 0
	global_load_lds_dwordx4 v182, s[6:7]
	s_waitcnt vmcnt(8)
	s_waitcnt lgkmcnt(0)
	s_barrier
	s_waitcnt lgkmcnt(0)
	v_mfma_f32_16x16x32_bf16 v[130:133], v[114:117], v[184:187], v[130:133]
	v_mfma_f32_16x16x32_bf16 v[126:129], v[138:141], v[184:187], v[126:129]
	v_mfma_f32_16x16x32_bf16 v[110:113], v[114:117], v[206:209], v[110:113]
	v_mfma_f32_16x16x32_bf16 v[106:109], v[138:141], v[206:209], v[106:109]
	v_mfma_f32_16x16x32_bf16 v[94:97], v[114:117], v[214:217], v[94:97]
	v_mfma_f32_16x16x32_bf16 v[90:93], v[138:141], v[214:217], v[90:93]
	v_mfma_f32_16x16x32_bf16 v[78:81], v[114:117], v[222:225], v[78:81]
	v_mfma_f32_16x16x32_bf16 v[74:77], v[138:141], v[222:225], v[74:77]
	v_mfma_f32_16x16x32_bf16 v[130:133], v[134:137], v[188:191], v[130:133]
	v_mfma_f32_16x16x32_bf16 v[126:129], v[142:145], v[188:191], v[126:129]
	v_mfma_f32_16x16x32_bf16 v[110:113], v[134:137], v[210:213], v[110:113]
	v_mfma_f32_16x16x32_bf16 v[106:109], v[142:145], v[210:213], v[106:109]
	v_mfma_f32_16x16x32_bf16 v[94:97], v[134:137], v[218:221], v[94:97]
	v_mfma_f32_16x16x32_bf16 v[90:93], v[142:145], v[218:221], v[90:93]
	v_mfma_f32_16x16x32_bf16 v[78:81], v[134:137], v[226:229], v[78:81]
	v_mfma_f32_16x16x32_bf16 v[74:77], v[142:145], v[226:229], v[74:77]
	v_mfma_f32_16x16x32_bf16 v[122:125], v[146:149], v[184:187], v[122:125]
	v_mfma_f32_16x16x32_bf16 v[118:121], v[154:157], v[184:187], v[118:121]
	v_mfma_f32_16x16x32_bf16 v[102:105], v[146:149], v[206:209], v[102:105]
	v_mfma_f32_16x16x32_bf16 v[98:101], v[154:157], v[206:209], v[98:101]
	v_mfma_f32_16x16x32_bf16 v[86:89], v[146:149], v[214:217], v[86:89]
	v_mfma_f32_16x16x32_bf16 v[82:85], v[154:157], v[214:217], v[82:85]
	v_mfma_f32_16x16x32_bf16 v[70:73], v[146:149], v[222:225], v[70:73]
	v_mfma_f32_16x16x32_bf16 v[66:69], v[154:157], v[222:225], v[66:69]
	v_mfma_f32_16x16x32_bf16 v[122:125], v[150:153], v[188:191], v[122:125]
	v_mfma_f32_16x16x32_bf16 v[118:121], v[158:161], v[188:191], v[118:121]
	v_mfma_f32_16x16x32_bf16 v[102:105], v[150:153], v[210:213], v[102:105]
	v_mfma_f32_16x16x32_bf16 v[98:101], v[158:161], v[210:213], v[98:101]
	v_mfma_f32_16x16x32_bf16 v[86:89], v[150:153], v[218:221], v[86:89]
	v_mfma_f32_16x16x32_bf16 v[82:85], v[158:161], v[218:221], v[82:85]
	v_mfma_f32_16x16x32_bf16 v[70:73], v[150:153], v[226:229], v[70:73]
	v_mfma_f32_16x16x32_bf16 v[66:69], v[158:161], v[226:229], v[66:69]
	s_barrier
	s_add_i32 s0, s89, s79
	s_mov_b32 m0, s0
	ds_read_b128 v[184:187], v199 offset:16384
	ds_read_b128 v[188:191], v199 offset:17408
	ds_read_b128 v[206:209], v199 offset:18432
	ds_read_b128 v[210:213], v199 offset:19456
	ds_read_b128 v[214:217], v199 offset:20480
	ds_read_b128 v[218:221], v199 offset:21504
	ds_read_b128 v[222:225], v199 offset:22528
	ds_read_b128 v[226:229], v199 offset:23552
	global_load_lds_dwordx4 v164, s[8:9]
	s_add_i32 m0, s0, 0x2000
	s_add_u32 s62, s8, 0x40000
	s_addc_u32 s63, s9, 0
	s_add_i32 s0, s90, s79
	global_load_lds_dwordx4 v168, s[8:9]
	s_mov_b32 m0, s0
	s_nop 0
	global_load_lds_dwordx4 v164, s[62:63]
	s_add_i32 m0, s0, 0x2000
	s_nop 0
	global_load_lds_dwordx4 v168, s[62:63]
	s_mov_b32 m0, s31
	s_nop 0
	global_load_lds_dwordx4 v162, s[10:11]
	s_mov_b32 m0, s80
	s_nop 0
	global_load_lds_dwordx4 v166, s[10:11]
	s_waitcnt vmcnt(8)
	s_waitcnt lgkmcnt(0)
	s_barrier
	s_waitcnt lgkmcnt(0)
	v_mfma_f32_16x16x32_bf16 v[62:65], v[114:117], v[184:187], v[62:65]
	v_mfma_f32_16x16x32_bf16 v[58:61], v[138:141], v[184:187], v[58:61]
	v_mfma_f32_16x16x32_bf16 v[46:49], v[114:117], v[206:209], v[46:49]
	v_mfma_f32_16x16x32_bf16 v[42:45], v[138:141], v[206:209], v[42:45]
	v_mfma_f32_16x16x32_bf16 v[30:33], v[114:117], v[214:217], v[30:33]
	v_mfma_f32_16x16x32_bf16 v[26:29], v[138:141], v[214:217], v[26:29]
	v_mfma_f32_16x16x32_bf16 v[14:17], v[114:117], v[222:225], v[14:17]
	v_mfma_f32_16x16x32_bf16 v[10:13], v[138:141], v[222:225], v[10:13]
	v_mfma_f32_16x16x32_bf16 v[62:65], v[134:137], v[188:191], v[62:65]
	v_mfma_f32_16x16x32_bf16 v[58:61], v[142:145], v[188:191], v[58:61]
	v_mfma_f32_16x16x32_bf16 v[46:49], v[134:137], v[210:213], v[46:49]
	v_mfma_f32_16x16x32_bf16 v[42:45], v[142:145], v[210:213], v[42:45]
	v_mfma_f32_16x16x32_bf16 v[30:33], v[134:137], v[218:221], v[30:33]
	v_mfma_f32_16x16x32_bf16 v[26:29], v[142:145], v[218:221], v[26:29]
	v_mfma_f32_16x16x32_bf16 v[14:17], v[134:137], v[226:229], v[14:17]
	v_mfma_f32_16x16x32_bf16 v[10:13], v[142:145], v[226:229], v[10:13]
	v_mfma_f32_16x16x32_bf16 v[54:57], v[146:149], v[184:187], v[54:57]
	v_mfma_f32_16x16x32_bf16 v[50:53], v[154:157], v[184:187], v[50:53]
	v_mfma_f32_16x16x32_bf16 v[38:41], v[146:149], v[206:209], v[38:41]
	v_mfma_f32_16x16x32_bf16 v[34:37], v[154:157], v[206:209], v[34:37]
	v_mfma_f32_16x16x32_bf16 v[22:25], v[146:149], v[214:217], v[22:25]
	v_mfma_f32_16x16x32_bf16 v[18:21], v[154:157], v[214:217], v[18:21]
	v_mfma_f32_16x16x32_bf16 v[6:9], v[146:149], v[222:225], v[6:9]
	v_mfma_f32_16x16x32_bf16 v[2:5], v[154:157], v[222:225], v[2:5]
	v_mfma_f32_16x16x32_bf16 v[54:57], v[150:153], v[188:191], v[54:57]
	v_mfma_f32_16x16x32_bf16 v[50:53], v[158:161], v[188:191], v[50:53]
	v_mfma_f32_16x16x32_bf16 v[38:41], v[150:153], v[210:213], v[38:41]
	v_mfma_f32_16x16x32_bf16 v[34:37], v[158:161], v[210:213], v[34:37]
	v_mfma_f32_16x16x32_bf16 v[22:25], v[150:153], v[218:221], v[22:25]
	v_mfma_f32_16x16x32_bf16 v[18:21], v[158:161], v[218:221], v[18:21]
	v_mfma_f32_16x16x32_bf16 v[6:9], v[150:153], v[226:229], v[6:9]
	v_mfma_f32_16x16x32_bf16 v[2:5], v[158:161], v[226:229], v[2:5]
	s_barrier
	s_add_i32 s0, 0, 0x18000
	s_add_i32 s27, 0, 0x1c000
	v_add_u32_e32 v142, s0, v173
	v_add_u32_e32 v158, s27, v173
	ds_read_b128 v[114:117], v142
	ds_read_b128 v[134:137], v142 offset:1024
	ds_read_b128 v[138:141], v142 offset:2048
	ds_read_b128 v[142:145], v142 offset:3072
	ds_read_b128 v[146:149], v158
	ds_read_b128 v[150:153], v158 offset:1024
	ds_read_b128 v[154:157], v158 offset:2048
	ds_read_b128 v[158:161], v158 offset:3072
	s_add_u32 s10, s10, 0x40000
	s_addc_u32 s11, s11, 0
	s_mov_b32 m0, s81
	ds_read_b128 v[184:187], v199 offset:32768
	ds_read_b128 v[188:191], v199 offset:33792
	ds_read_b128 v[206:209], v199 offset:34816
	ds_read_b128 v[210:213], v199 offset:35840
	ds_read_b128 v[214:217], v199 offset:36864
	ds_read_b128 v[218:221], v199 offset:37888
	ds_read_b128 v[222:225], v199 offset:38912
	ds_read_b128 v[226:229], v199 offset:39936
	global_load_lds_dwordx4 v162, s[10:11]
	s_mov_b32 m0, s82
	s_nop 0
	global_load_lds_dwordx4 v166, s[10:11]
	s_waitcnt vmcnt(8)
	s_waitcnt lgkmcnt(0)
	s_barrier
	s_waitcnt lgkmcnt(0)
	v_mfma_f32_16x16x32_bf16 v[130:133], v[114:117], v[184:187], v[130:133]
	v_mfma_f32_16x16x32_bf16 v[126:129], v[138:141], v[184:187], v[126:129]
	v_mfma_f32_16x16x32_bf16 v[110:113], v[114:117], v[206:209], v[110:113]
	v_mfma_f32_16x16x32_bf16 v[106:109], v[138:141], v[206:209], v[106:109]
	v_mfma_f32_16x16x32_bf16 v[94:97], v[114:117], v[214:217], v[94:97]
	v_mfma_f32_16x16x32_bf16 v[90:93], v[138:141], v[214:217], v[90:93]
	v_mfma_f32_16x16x32_bf16 v[78:81], v[114:117], v[222:225], v[78:81]
	v_mfma_f32_16x16x32_bf16 v[74:77], v[138:141], v[222:225], v[74:77]
	v_mfma_f32_16x16x32_bf16 v[130:133], v[134:137], v[188:191], v[130:133]
	v_mfma_f32_16x16x32_bf16 v[126:129], v[142:145], v[188:191], v[126:129]
	v_mfma_f32_16x16x32_bf16 v[110:113], v[134:137], v[210:213], v[110:113]
	v_mfma_f32_16x16x32_bf16 v[106:109], v[142:145], v[210:213], v[106:109]
	v_mfma_f32_16x16x32_bf16 v[94:97], v[134:137], v[218:221], v[94:97]
	v_mfma_f32_16x16x32_bf16 v[90:93], v[142:145], v[218:221], v[90:93]
	v_mfma_f32_16x16x32_bf16 v[78:81], v[134:137], v[226:229], v[78:81]
	v_mfma_f32_16x16x32_bf16 v[74:77], v[142:145], v[226:229], v[74:77]
	v_mfma_f32_16x16x32_bf16 v[122:125], v[146:149], v[184:187], v[122:125]
	v_mfma_f32_16x16x32_bf16 v[118:121], v[154:157], v[184:187], v[118:121]
	v_mfma_f32_16x16x32_bf16 v[102:105], v[146:149], v[206:209], v[102:105]
	v_mfma_f32_16x16x32_bf16 v[98:101], v[154:157], v[206:209], v[98:101]
	v_mfma_f32_16x16x32_bf16 v[86:89], v[146:149], v[214:217], v[86:89]
	v_mfma_f32_16x16x32_bf16 v[82:85], v[154:157], v[214:217], v[82:85]
	v_mfma_f32_16x16x32_bf16 v[70:73], v[146:149], v[222:225], v[70:73]
	v_mfma_f32_16x16x32_bf16 v[66:69], v[154:157], v[222:225], v[66:69]
	v_mfma_f32_16x16x32_bf16 v[122:125], v[150:153], v[188:191], v[122:125]
	v_mfma_f32_16x16x32_bf16 v[118:121], v[158:161], v[188:191], v[118:121]
	v_mfma_f32_16x16x32_bf16 v[102:105], v[150:153], v[210:213], v[102:105]
	v_mfma_f32_16x16x32_bf16 v[98:101], v[158:161], v[210:213], v[98:101]
	v_mfma_f32_16x16x32_bf16 v[86:89], v[150:153], v[218:221], v[86:89]
	v_mfma_f32_16x16x32_bf16 v[82:85], v[158:161], v[218:221], v[82:85]
	v_mfma_f32_16x16x32_bf16 v[70:73], v[150:153], v[226:229], v[70:73]
	v_mfma_f32_16x16x32_bf16 v[66:69], v[158:161], v[226:229], v[66:69]
	s_barrier
	s_add_i32 s0, s0, s79
	s_mov_b32 m0, s0
	ds_read_b128 v[184:187], v199 offset:49152
	ds_read_b128 v[188:191], v199 offset:50176
	ds_read_b128 v[206:209], v199 offset:51200
	ds_read_b128 v[210:213], v199 offset:52224
	ds_read_b128 v[214:217], v199 offset:53248
	ds_read_b128 v[218:221], v199 offset:54272
	ds_read_b128 v[222:225], v199 offset:55296
	ds_read_b128 v[226:229], v199 offset:56320
	s_add_u32 s98, s8, 0x80
	s_addc_u32 s99, s9, 0
	global_load_lds_dwordx4 v164, s[98:99]
	s_add_i32 m0, s0, 0x2000
	s_add_u32 s8, s8, 0x40080
	s_addc_u32 s9, s9, 0
	s_add_i32 s0, s27, s79
	global_load_lds_dwordx4 v168, s[98:99]
	s_mov_b32 m0, s0
	s_nop 0
	global_load_lds_dwordx4 v164, s[8:9]
	s_add_i32 m0, s0, 0x2000
	s_nop 0
	global_load_lds_dwordx4 v168, s[8:9]
	s_add_u32 s98, s10, 0xfffc0080
	s_addc_u32 s99, s11, -1
	s_mov_b32 m0, s84
	s_nop 0
	global_load_lds_dwordx4 v162, s[98:99]
	s_mov_b32 m0, s85
	s_nop 0
	global_load_lds_dwordx4 v166, s[98:99]
	s_waitcnt vmcnt(8)
	s_waitcnt lgkmcnt(0)
	s_barrier
	s_waitcnt lgkmcnt(0)
	v_mfma_f32_16x16x32_bf16 v[62:65], v[114:117], v[184:187], v[62:65]
	v_mfma_f32_16x16x32_bf16 v[58:61], v[138:141], v[184:187], v[58:61]
	v_mfma_f32_16x16x32_bf16 v[46:49], v[114:117], v[206:209], v[46:49]
	v_mfma_f32_16x16x32_bf16 v[42:45], v[138:141], v[206:209], v[42:45]
	v_mfma_f32_16x16x32_bf16 v[30:33], v[114:117], v[214:217], v[30:33]
	v_mfma_f32_16x16x32_bf16 v[26:29], v[138:141], v[214:217], v[26:29]
	v_mfma_f32_16x16x32_bf16 v[14:17], v[114:117], v[222:225], v[14:17]
	v_mfma_f32_16x16x32_bf16 v[10:13], v[138:141], v[222:225], v[10:13]
	v_mfma_f32_16x16x32_bf16 v[62:65], v[134:137], v[188:191], v[62:65]
	v_mfma_f32_16x16x32_bf16 v[58:61], v[142:145], v[188:191], v[58:61]
	v_mfma_f32_16x16x32_bf16 v[46:49], v[134:137], v[210:213], v[46:49]
	v_mfma_f32_16x16x32_bf16 v[42:45], v[142:145], v[210:213], v[42:45]
	v_mfma_f32_16x16x32_bf16 v[30:33], v[134:137], v[218:221], v[30:33]
	v_mfma_f32_16x16x32_bf16 v[26:29], v[142:145], v[218:221], v[26:29]
	v_mfma_f32_16x16x32_bf16 v[14:17], v[134:137], v[226:229], v[14:17]
	v_mfma_f32_16x16x32_bf16 v[10:13], v[142:145], v[226:229], v[10:13]
	v_mfma_f32_16x16x32_bf16 v[54:57], v[146:149], v[184:187], v[54:57]
	v_mfma_f32_16x16x32_bf16 v[50:53], v[154:157], v[184:187], v[50:53]
	v_mfma_f32_16x16x32_bf16 v[38:41], v[146:149], v[206:209], v[38:41]
	v_mfma_f32_16x16x32_bf16 v[34:37], v[154:157], v[206:209], v[34:37]
	v_mfma_f32_16x16x32_bf16 v[22:25], v[146:149], v[214:217], v[22:25]
	v_mfma_f32_16x16x32_bf16 v[18:21], v[154:157], v[214:217], v[18:21]
	v_mfma_f32_16x16x32_bf16 v[6:9], v[146:149], v[222:225], v[6:9]
	v_mfma_f32_16x16x32_bf16 v[2:5], v[154:157], v[222:225], v[2:5]
	v_mfma_f32_16x16x32_bf16 v[54:57], v[150:153], v[188:191], v[54:57]
	v_mfma_f32_16x16x32_bf16 v[50:53], v[158:161], v[188:191], v[50:53]
	v_mfma_f32_16x16x32_bf16 v[38:41], v[150:153], v[210:213], v[38:41]
	v_mfma_f32_16x16x32_bf16 v[34:37], v[158:161], v[210:213], v[34:37]
	v_mfma_f32_16x16x32_bf16 v[22:25], v[150:153], v[218:221], v[22:25]
	v_mfma_f32_16x16x32_bf16 v[18:21], v[158:161], v[218:221], v[18:21]
	v_mfma_f32_16x16x32_bf16 v[6:9], v[150:153], v[226:229], v[6:9]
	v_mfma_f32_16x16x32_bf16 v[2:5], v[158:161], v[226:229], v[2:5]
	s_barrier
	s_add_i32 s26, s26, 2
	s_add_u32 s6, s6, 0x100
	s_addc_u32 s7, s7, 0
	s_add_u32 s24, s24, 0x100
	s_addc_u32 s25, s25, 0
	s_cmp_gt_u32 s26, 13
	s_cbranch_scc0 .LBB0_368
	s_and_b64 vcc, exec, s[46:47]
	s_cbranch_vccz .LBB0_371

.LBB0_658:
	s_setprio 0
	s_waitcnt vmcnt(0)
	s_barrier
	s_waitcnt vmcnt(0)
	v_readlane_b32 s80, v246, 5
	v_readlane_b32 s81, v246, 6
	s_waitcnt vmcnt(0)
	s_barrier
	s_and_saveexec_b64 s[6:7], s[80:81]
	v_readlane_b32 s88, v246, 10
	v_readlane_b32 s86, v246, 7
	v_readlane_b32 s79, v246, 9
	v_readlane_b32 s89, v246, 11
	v_readlane_b32 s62, v246, 12
	v_readlane_b32 s63, v246, 19
	v_readlane_b32 s87, v246, 8
	s_cbranch_execz .LBB0_682
	s_add_i32 s0, 0, 0x2016c
	v_mov_b32_e32 v1, s0
	s_waitcnt vmcnt(0) expcnt(0) lgkmcnt(0)
	ds_read_b32 v1, v1
	s_waitcnt lgkmcnt(0)
	v_cmp_ne_u32_e32 vcc, 0, v1
	s_cbranch_vccnz .LBB0_661
	buffer_wbl2 sc1
	s_waitcnt vmcnt(0)

.LBB0_815:
	s_or_b64 exec, exec, s[6:7]
	v_readlane_b32 s0, v246, 2
	v_readlane_b32 s1, v246, 3
	s_add_u32 s26, s0, 0x2400000
	s_addc_u32 s27, s1, 0
	s_movk_i32 s6, 0x500
	s_add_u32 s2, s0, 0xe00000
	v_bfe_u32 v3, v0, 3, 25
	s_movk_i32 s5, 0x60
	s_barrier
	s_addc_u32 s3, s1, 0
	s_ashr_i32 s31, s86, 1
	s_ashr_i32 s7, s6, 31
	v_lshlrev_b32_e32 v2, 4, v0
	v_bitop3_b32 v22, v3, s5, 64 bitop3:0xc8
	v_and_b32_e32 v5, 32, v0
	s_movk_i32 s5, 0x70
	s_and_b32 s1, s31, -2
	s_lshl_b64 s[10:11], s[6:7], 9
	v_bitop3_b32 v14, v2, v5, 48 bitop3:0x6c
	v_and_b32_e32 v15, 64, v0
	v_bitop3_b32 v20, v3, s5, 64 bitop3:0xc8
	v_bfe_u32 v19, v0, 2, 4
	s_ashr_i32 s5, s31, 31
	v_lshrrev_b32_e32 v1, 5, v0
	v_or_b32_e32 v2, v14, v15
	v_or_b32_e32 v3, v20, v19
	s_mul_i32 s29, s10, s5
	s_mul_hi_u32 s5, s10, s1
	s_lshr_b64 s[12:13], s[6:7], 23
	s_and_b32 s0, s86, 3
	v_readfirstlane_b32 s24, v0
	v_and_b32_e32 v16, 4, v1
	v_lshrrev_b32_e32 v1, 1, v0
	v_lshrrev_b32_e32 v2, 1, v2
	v_mul_lo_u32 v3, s6, v3
	s_add_i32 s5, s5, s29
	s_mul_i32 s13, s12, s1
	s_lshr_b32 s25, s24, 6
	v_bfe_u32 v17, v0, 2, 2
	v_and_b32_e32 v18, 24, v1
	v_add_lshl_u32 v132, v3, v2, 1
	v_lshrrev_b32_e32 v3, 3, v0
	s_add_i32 s13, s5, s13
	s_mul_i32 s5, s12, s0
	s_mul_hi_u32 s12, s10, s0
	s_lshr_b32 s28, s24, 8
	s_lshl_b64 s[8:9], s[6:7], 8
	s_lshl_b32 s4, s25, 10
	v_or3_b32 v1, v16, v17, v18
	v_and_b32_e32 v23, 32, v3
	s_add_i32 s12, s12, s5
	s_mul_i32 s5, s10, s0
	v_or_b32_e32 v4, v1, v22
	v_or_b32_e32 v1, v1, v23
	s_add_u32 s36, s2, s5
	v_mul_lo_u32 v1, s6, v1
	s_addc_u32 s37, s3, s12
	s_add_i32 s5, s4, 0
	v_add_lshl_u32 v134, v1, v2, 1
	s_add_i32 m0, s5, 0x10000
	v_mul_lo_u32 v4, s6, v4
	global_load_lds_dwordx4 v134, s[36:37]
	s_add_i32 m0, s5, 0x12000
	v_add_lshl_u32 v130, v4, v2, 1
	s_add_u32 s14, s36, s8
	global_load_lds_dwordx4 v130, s[36:37]
	s_addc_u32 s15, s37, s9
	s_add_i32 m0, s5, 0x14000
	v_and_b32_e32 v21, 48, v3
	s_mul_i32 s16, s10, s1
	global_load_lds_dwordx4 v134, s[14:15]
	s_add_i32 m0, s5, 0x16000
	v_or_b32_e32 v1, v21, v19
	s_add_u32 s12, s26, s16
	v_mul_lo_u32 v1, s6, v1
	s_addc_u32 s13, s27, s13
	s_add_i32 s46, s5, 0x2000
	v_add_lshl_u32 v136, v1, v2, 1
	global_load_lds_dwordx4 v130, s[14:15]
	s_mov_b32 m0, s5
	s_add_u32 s16, s12, s8
	global_load_lds_dwordx4 v136, s[12:13]
	s_mov_b32 m0, s46
	s_addc_u32 s17, s13, s9
	s_add_i32 s47, s5, 0x4000
	global_load_lds_dwordx4 v132, s[12:13]
	s_mov_b32 m0, s47
	s_add_i32 s48, s5, 0x6000
	global_load_lds_dwordx4 v136, s[16:17]
	s_mov_b32 m0, s48
	v_mov_b32_e32 v139, 0
	global_load_lds_dwordx4 v132, s[16:17]
	v_mov_b32_e32 v135, v139
	v_mov_b32_e32 v131, v139
	v_mov_b32_e32 v137, v139
	v_mov_b32_e32 v133, v139
	s_cmp_eq_u32 s28, 1
	s_mov_b32 s38, 4
	v_lshl_add_u64 v[10:11], s[36:37], 0, v[134:135]
	v_lshl_add_u64 v[6:7], s[36:37], 0, v[130:131]
	v_lshl_add_u64 v[4:5], s[14:15], 0, v[134:135]
	v_lshl_add_u64 v[2:3], s[14:15], 0, v[130:131]
	v_lshl_add_u64 v[8:9], s[12:13], 0, v[136:137]
	s_cselect_b64 s[14:15], -1, 0
	s_cmp_lg_u32 s28, 1
	v_lshl_add_u64 v[12:13], s[12:13], 0, v[132:133]
	s_cbranch_scc1 .LBB0_817
	s_barrier
	s_setprio 1

.LBB0_824:
	ds_read_b128 v[156:159], v185
	ds_read_b128 v[160:163], v185 offset:1024
	ds_read_b128 v[164:167], v185 offset:2048
	ds_read_b128 v[168:171], v185 offset:3072
	ds_read_b128 v[172:175], v186
	ds_read_b128 v[188:191], v186 offset:1024
	ds_read_b128 v[192:195], v186 offset:2048
	ds_read_b128 v[196:199], v186 offset:3072
	s_add_i32 s41, s41, 2
	v_lshl_add_u64 v[176:177], s[38:39], 0, v[154:155]
	v_lshl_add_u64 v[176:177], v[176:177], 0, s[44:45]
	v_lshl_add_u64 v[182:183], v[176:177], 0, s[22:23]
	s_add_i32 m0, s5, 0xc000
	ds_read_b128 v[200:203], v187
	ds_read_b128 v[204:207], v187 offset:1024
	ds_read_b128 v[208:211], v187 offset:2048
	ds_read_b128 v[212:215], v187 offset:3072
	ds_read_b128 v[216:219], v187 offset:4096
	ds_read_b128 v[220:223], v187 offset:5120
	ds_read_b128 v[224:227], v187 offset:6144
	ds_read_b128 v[228:231], v187 offset:7168
	global_load_lds_dwordx4 v[182:183], off
	v_lshl_add_u64 v[182:183], s[38:39], 0, v[150:151]
	v_lshl_add_u64 v[182:183], v[182:183], 0, s[44:45]
	v_lshl_add_u64 v[232:233], v[182:183], 0, s[22:23]
	s_add_i32 m0, s5, 0xe000
	s_nop 0
	global_load_lds_dwordx4 v[232:233], off
	s_waitcnt vmcnt(8)
	s_waitcnt lgkmcnt(0)
	s_barrier
	s_waitcnt lgkmcnt(0)
	v_mfma_f32_16x16x32_bf16 v[70:73], v[156:159], v[200:203], v[70:73]
	v_mfma_f32_16x16x32_bf16 v[66:69], v[164:167], v[200:203], v[66:69]
	v_mfma_f32_16x16x32_bf16 v[86:89], v[156:159], v[208:211], v[86:89]
	v_mfma_f32_16x16x32_bf16 v[94:97], v[164:167], v[208:211], v[94:97]
	v_mfma_f32_16x16x32_bf16 v[110:113], v[156:159], v[216:219], v[110:113]
	v_mfma_f32_16x16x32_bf16 v[114:117], v[164:167], v[216:219], v[114:117]
	v_mfma_f32_16x16x32_bf16 v[126:129], v[156:159], v[224:227], v[126:129]
	v_mfma_f32_16x16x32_bf16 v[102:105], v[164:167], v[224:227], v[102:105]
	v_mfma_f32_16x16x32_bf16 v[70:73], v[160:163], v[204:207], v[70:73]
	v_mfma_f32_16x16x32_bf16 v[66:69], v[168:171], v[204:207], v[66:69]
	v_mfma_f32_16x16x32_bf16 v[86:89], v[160:163], v[212:215], v[86:89]
	v_mfma_f32_16x16x32_bf16 v[94:97], v[168:171], v[212:215], v[94:97]
	v_mfma_f32_16x16x32_bf16 v[110:113], v[160:163], v[220:223], v[110:113]
	v_mfma_f32_16x16x32_bf16 v[114:117], v[168:171], v[220:223], v[114:117]
	v_mfma_f32_16x16x32_bf16 v[126:129], v[160:163], v[228:231], v[126:129]
	v_mfma_f32_16x16x32_bf16 v[102:105], v[168:171], v[228:231], v[102:105]
	v_mfma_f32_16x16x32_bf16 v[74:77], v[172:175], v[200:203], v[74:77]
	v_mfma_f32_16x16x32_bf16 v[82:85], v[192:195], v[200:203], v[82:85]
	v_mfma_f32_16x16x32_bf16 v[98:101], v[172:175], v[208:211], v[98:101]
	v_mfma_f32_16x16x32_bf16 v[106:109], v[192:195], v[208:211], v[106:109]
	v_mfma_f32_16x16x32_bf16 v[118:121], v[172:175], v[216:219], v[118:121]
	v_mfma_f32_16x16x32_bf16 v[122:125], v[192:195], v[216:219], v[122:125]
	v_mfma_f32_16x16x32_bf16 v[90:93], v[172:175], v[224:227], v[90:93]
	v_mfma_f32_16x16x32_bf16 v[78:81], v[192:195], v[224:227], v[78:81]
	v_mfma_f32_16x16x32_bf16 v[74:77], v[188:191], v[204:207], v[74:77]
	v_mfma_f32_16x16x32_bf16 v[82:85], v[196:199], v[204:207], v[82:85]
	v_mfma_f32_16x16x32_bf16 v[98:101], v[188:191], v[212:215], v[98:101]
	v_mfma_f32_16x16x32_bf16 v[106:109], v[196:199], v[212:215], v[106:109]
	v_mfma_f32_16x16x32_bf16 v[118:121], v[188:191], v[220:223], v[118:121]
	v_mfma_f32_16x16x32_bf16 v[122:125], v[196:199], v[220:223], v[122:125]
	v_mfma_f32_16x16x32_bf16 v[90:93], v[188:191], v[228:231], v[90:93]
	v_mfma_f32_16x16x32_bf16 v[78:81], v[196:199], v[228:231], v[78:81]
	s_barrier
	v_lshl_add_u64 v[232:233], s[36:37], 0, v[144:145]
	v_lshl_add_u64 v[232:233], v[232:233], 0, s[44:45]
	s_add_i32 s60, s57, s4
	v_lshl_add_u64 v[234:235], v[232:233], 0, s[26:27]
	s_mov_b32 m0, s60
	ds_read_b128 v[200:203], v187 offset:16384
	ds_read_b128 v[204:207], v187 offset:17408
	ds_read_b128 v[208:211], v187 offset:18432
	ds_read_b128 v[212:215], v187 offset:19456
	ds_read_b128 v[216:219], v187 offset:20480
	ds_read_b128 v[220:223], v187 offset:21504
	ds_read_b128 v[224:227], v187 offset:22528
	ds_read_b128 v[228:231], v187 offset:23552
	global_load_lds_dwordx4 v[234:235], off
	v_lshl_add_u64 v[234:235], s[36:37], 0, v[140:141]
	v_lshl_add_u64 v[234:235], v[234:235], 0, s[44:45]
	v_lshl_add_u64 v[236:237], v[234:235], 0, s[26:27]
	s_add_i32 m0, s60, 0x2000
	s_add_i32 s60, s58, s4
	global_load_lds_dwordx4 v[236:237], off
	v_lshl_add_u64 v[236:237], s[36:37], 0, v[146:147]
	v_lshl_add_u64 v[236:237], v[236:237], 0, s[44:45]
	v_lshl_add_u64 v[238:239], v[236:237], 0, s[26:27]
	s_mov_b32 m0, s60
	s_nop 0
	global_load_lds_dwordx4 v[238:239], off
	v_lshl_add_u64 v[238:239], s[36:37], 0, v[142:143]
	v_lshl_add_u64 v[238:239], v[238:239], 0, s[44:45]
	v_lshl_add_u64 v[240:241], v[238:239], 0, s[26:27]
	s_add_i32 m0, s60, 0x2000
	s_nop 0
	global_load_lds_dwordx4 v[240:241], off
	v_lshl_add_u64 v[240:241], s[38:39], 0, v[152:153]
	v_lshl_add_u64 v[240:241], v[240:241], 0, s[44:45]
	v_lshl_add_u64 v[242:243], v[240:241], 0, s[26:27]
	s_mov_b32 m0, s5
	s_nop 0
	global_load_lds_dwordx4 v[242:243], off
	v_lshl_add_u64 v[242:243], s[38:39], 0, v[148:149]
	v_lshl_add_u64 v[242:243], v[242:243], 0, s[44:45]
	v_lshl_add_u64 v[244:245], v[242:243], 0, s[26:27]
	s_mov_b32 m0, s46
	s_nop 0
	global_load_lds_dwordx4 v[244:245], off
	s_waitcnt vmcnt(8)
	s_waitcnt lgkmcnt(0)
	s_barrier
	s_waitcnt lgkmcnt(0)
	v_mfma_f32_16x16x32_bf16 v[62:65], v[156:159], v[200:203], v[62:65]
	v_mfma_f32_16x16x32_bf16 v[58:61], v[164:167], v[200:203], v[58:61]
	v_mfma_f32_16x16x32_bf16 v[46:49], v[156:159], v[208:211], v[46:49]
	v_mfma_f32_16x16x32_bf16 v[42:45], v[164:167], v[208:211], v[42:45]
	v_mfma_f32_16x16x32_bf16 v[30:33], v[156:159], v[216:219], v[30:33]
	v_mfma_f32_16x16x32_bf16 v[26:29], v[164:167], v[216:219], v[26:29]
	v_mfma_f32_16x16x32_bf16 v[14:17], v[156:159], v[224:227], v[14:17]
	v_mfma_f32_16x16x32_bf16 v[10:13], v[164:167], v[224:227], v[10:13]
	v_mfma_f32_16x16x32_bf16 v[62:65], v[160:163], v[204:207], v[62:65]
	v_mfma_f32_16x16x32_bf16 v[58:61], v[168:171], v[204:207], v[58:61]
	v_mfma_f32_16x16x32_bf16 v[46:49], v[160:163], v[212:215], v[46:49]
	v_mfma_f32_16x16x32_bf16 v[42:45], v[168:171], v[212:215], v[42:45]
	v_mfma_f32_16x16x32_bf16 v[30:33], v[160:163], v[220:223], v[30:33]
	v_mfma_f32_16x16x32_bf16 v[26:29], v[168:171], v[220:223], v[26:29]
	v_mfma_f32_16x16x32_bf16 v[14:17], v[160:163], v[228:231], v[14:17]
	v_mfma_f32_16x16x32_bf16 v[10:13], v[168:171], v[228:231], v[10:13]
	v_mfma_f32_16x16x32_bf16 v[54:57], v[172:175], v[200:203], v[54:57]
	v_mfma_f32_16x16x32_bf16 v[50:53], v[192:195], v[200:203], v[50:53]
	v_mfma_f32_16x16x32_bf16 v[38:41], v[172:175], v[208:211], v[38:41]
	v_mfma_f32_16x16x32_bf16 v[34:37], v[192:195], v[208:211], v[34:37]
	v_mfma_f32_16x16x32_bf16 v[22:25], v[172:175], v[216:219], v[22:25]
	v_mfma_f32_16x16x32_bf16 v[18:21], v[192:195], v[216:219], v[18:21]
	v_mfma_f32_16x16x32_bf16 v[6:9], v[172:175], v[224:227], v[6:9]
	v_mfma_f32_16x16x32_bf16 v[2:5], v[192:195], v[224:227], v[2:5]
	v_mfma_f32_16x16x32_bf16 v[54:57], v[188:191], v[204:207], v[54:57]
	v_mfma_f32_16x16x32_bf16 v[50:53], v[196:199], v[204:207], v[50:53]
	v_mfma_f32_16x16x32_bf16 v[38:41], v[188:191], v[212:215], v[38:41]
	v_mfma_f32_16x16x32_bf16 v[34:37], v[196:199], v[212:215], v[34:37]
	v_mfma_f32_16x16x32_bf16 v[22:25], v[188:191], v[220:223], v[22:25]
	v_mfma_f32_16x16x32_bf16 v[18:21], v[196:199], v[220:223], v[18:21]
	v_mfma_f32_16x16x32_bf16 v[6:9], v[188:191], v[228:231], v[6:9]
	v_mfma_f32_16x16x32_bf16 v[2:5], v[196:199], v[228:231], v[2:5]
	s_barrier
	s_add_i32 s60, 0, 0x18000
	v_add_u32_e32 v138, s60, v181
	s_add_i32 s61, 0, 0x1c000
	ds_read_b128 v[156:159], v138
	ds_read_b128 v[160:163], v138 offset:1024
	ds_read_b128 v[164:167], v138 offset:2048
	ds_read_b128 v[168:171], v138 offset:3072
	v_add_u32_e32 v138, s61, v181
	ds_read_b128 v[172:175], v138
	ds_read_b128 v[188:191], v138 offset:1024
	ds_read_b128 v[192:195], v138 offset:2048
	ds_read_b128 v[196:199], v138 offset:3072
	s_mov_b32 m0, s47
	v_lshl_add_u64 v[176:177], v[176:177], 0, s[26:27]
	ds_read_b128 v[200:203], v187 offset:32768
	ds_read_b128 v[204:207], v187 offset:33792
	ds_read_b128 v[208:211], v187 offset:34816
	ds_read_b128 v[212:215], v187 offset:35840
	ds_read_b128 v[216:219], v187 offset:36864
	ds_read_b128 v[220:223], v187 offset:37888
	ds_read_b128 v[224:227], v187 offset:38912
	ds_read_b128 v[228:231], v187 offset:39936
	global_load_lds_dwordx4 v[176:177], off
	v_lshl_add_u64 v[176:177], v[182:183], 0, s[26:27]
	s_mov_b32 m0, s48
	s_nop 0
	global_load_lds_dwordx4 v[176:177], off
	s_waitcnt vmcnt(8)
	s_waitcnt lgkmcnt(0)
	s_barrier
	s_waitcnt lgkmcnt(0)
	v_mfma_f32_16x16x32_bf16 v[70:73], v[156:159], v[200:203], v[70:73]
	v_mfma_f32_16x16x32_bf16 v[66:69], v[164:167], v[200:203], v[66:69]
	v_mfma_f32_16x16x32_bf16 v[86:89], v[156:159], v[208:211], v[86:89]
	v_mfma_f32_16x16x32_bf16 v[94:97], v[164:167], v[208:211], v[94:97]
	v_mfma_f32_16x16x32_bf16 v[110:113], v[156:159], v[216:219], v[110:113]
	v_mfma_f32_16x16x32_bf16 v[114:117], v[164:167], v[216:219], v[114:117]
	v_mfma_f32_16x16x32_bf16 v[126:129], v[156:159], v[224:227], v[126:129]
	v_mfma_f32_16x16x32_bf16 v[102:105], v[164:167], v[224:227], v[102:105]
	v_mfma_f32_16x16x32_bf16 v[70:73], v[160:163], v[204:207], v[70:73]
	v_mfma_f32_16x16x32_bf16 v[66:69], v[168:171], v[204:207], v[66:69]
	v_mfma_f32_16x16x32_bf16 v[86:89], v[160:163], v[212:215], v[86:89]
	v_mfma_f32_16x16x32_bf16 v[94:97], v[168:171], v[212:215], v[94:97]
	v_mfma_f32_16x16x32_bf16 v[110:113], v[160:163], v[220:223], v[110:113]
	v_mfma_f32_16x16x32_bf16 v[114:117], v[168:171], v[220:223], v[114:117]
	v_mfma_f32_16x16x32_bf16 v[126:129], v[160:163], v[228:231], v[126:129]
	v_mfma_f32_16x16x32_bf16 v[102:105], v[168:171], v[228:231], v[102:105]
	v_mfma_f32_16x16x32_bf16 v[74:77], v[172:175], v[200:203], v[74:77]
	v_mfma_f32_16x16x32_bf16 v[82:85], v[192:195], v[200:203], v[82:85]
	v_mfma_f32_16x16x32_bf16 v[98:101], v[172:175], v[208:211], v[98:101]
	v_mfma_f32_16x16x32_bf16 v[106:109], v[192:195], v[208:211], v[106:109]
	v_mfma_f32_16x16x32_bf16 v[118:121], v[172:175], v[216:219], v[118:121]
	v_mfma_f32_16x16x32_bf16 v[122:125], v[192:195], v[216:219], v[122:125]
	v_mfma_f32_16x16x32_bf16 v[90:93], v[172:175], v[224:227], v[90:93]
	v_mfma_f32_16x16x32_bf16 v[78:81], v[192:195], v[224:227], v[78:81]
	v_mfma_f32_16x16x32_bf16 v[74:77], v[188:191], v[204:207], v[74:77]
	v_mfma_f32_16x16x32_bf16 v[82:85], v[196:199], v[204:207], v[82:85]
	v_mfma_f32_16x16x32_bf16 v[98:101], v[188:191], v[212:215], v[98:101]
	v_mfma_f32_16x16x32_bf16 v[106:109], v[196:199], v[212:215], v[106:109]
	v_mfma_f32_16x16x32_bf16 v[118:121], v[188:191], v[220:223], v[118:121]
	v_mfma_f32_16x16x32_bf16 v[122:125], v[196:199], v[220:223], v[122:125]
	v_mfma_f32_16x16x32_bf16 v[90:93], v[188:191], v[228:231], v[90:93]
	v_mfma_f32_16x16x32_bf16 v[78:81], v[196:199], v[228:231], v[78:81]
	s_barrier
	s_add_i32 s60, s60, s4
	v_lshl_add_u64 v[176:177], v[232:233], 0, s[28:29]
	s_mov_b32 m0, s60
	ds_read_b128 v[200:203], v187 offset:49152
	ds_read_b128 v[204:207], v187 offset:50176
	ds_read_b128 v[208:211], v187 offset:51200
	ds_read_b128 v[212:215], v187 offset:52224
	ds_read_b128 v[216:219], v187 offset:53248
	ds_read_b128 v[220:223], v187 offset:54272
	ds_read_b128 v[224:227], v187 offset:55296
	ds_read_b128 v[228:231], v187 offset:56320
	global_load_lds_dwordx4 v[176:177], off
	v_lshl_add_u64 v[176:177], v[234:235], 0, s[28:29]
	s_add_i32 m0, s60, 0x2000
	s_add_i32 s60, s61, s4
	global_load_lds_dwordx4 v[176:177], off
	v_lshl_add_u64 v[176:177], v[236:237], 0, s[28:29]
	s_mov_b32 m0, s60
	s_nop 0
	global_load_lds_dwordx4 v[176:177], off
	v_lshl_add_u64 v[176:177], v[238:239], 0, s[28:29]
	s_add_i32 m0, s60, 0x2000
	s_nop 0
	global_load_lds_dwordx4 v[176:177], off
	v_lshl_add_u64 v[176:177], v[240:241], 0, s[28:29]
	s_mov_b32 m0, s49
	s_nop 0
	global_load_lds_dwordx4 v[176:177], off
	v_lshl_add_u64 v[176:177], v[242:243], 0, s[28:29]
	s_mov_b32 m0, s50
	s_nop 0
	global_load_lds_dwordx4 v[176:177], off
	s_waitcnt vmcnt(8)
	s_waitcnt lgkmcnt(0)
	s_barrier
	s_waitcnt lgkmcnt(0)
	v_mfma_f32_16x16x32_bf16 v[62:65], v[156:159], v[200:203], v[62:65]
	v_mfma_f32_16x16x32_bf16 v[58:61], v[164:167], v[200:203], v[58:61]
	v_mfma_f32_16x16x32_bf16 v[46:49], v[156:159], v[208:211], v[46:49]
	v_mfma_f32_16x16x32_bf16 v[42:45], v[164:167], v[208:211], v[42:45]
	v_mfma_f32_16x16x32_bf16 v[30:33], v[156:159], v[216:219], v[30:33]
	v_mfma_f32_16x16x32_bf16 v[26:29], v[164:167], v[216:219], v[26:29]
	v_mfma_f32_16x16x32_bf16 v[14:17], v[156:159], v[224:227], v[14:17]
	v_mfma_f32_16x16x32_bf16 v[10:13], v[164:167], v[224:227], v[10:13]
	v_mfma_f32_16x16x32_bf16 v[62:65], v[160:163], v[204:207], v[62:65]
	v_mfma_f32_16x16x32_bf16 v[58:61], v[168:171], v[204:207], v[58:61]
	v_mfma_f32_16x16x32_bf16 v[46:49], v[160:163], v[212:215], v[46:49]
	v_mfma_f32_16x16x32_bf16 v[42:45], v[168:171], v[212:215], v[42:45]
	v_mfma_f32_16x16x32_bf16 v[30:33], v[160:163], v[220:223], v[30:33]
	v_mfma_f32_16x16x32_bf16 v[26:29], v[168:171], v[220:223], v[26:29]
	v_mfma_f32_16x16x32_bf16 v[14:17], v[160:163], v[228:231], v[14:17]
	v_mfma_f32_16x16x32_bf16 v[10:13], v[168:171], v[228:231], v[10:13]
	v_mfma_f32_16x16x32_bf16 v[54:57], v[172:175], v[200:203], v[54:57]
	v_mfma_f32_16x16x32_bf16 v[50:53], v[192:195], v[200:203], v[50:53]
	v_mfma_f32_16x16x32_bf16 v[38:41], v[172:175], v[208:211], v[38:41]
	v_mfma_f32_16x16x32_bf16 v[34:37], v[192:195], v[208:211], v[34:37]
	v_mfma_f32_16x16x32_bf16 v[22:25], v[172:175], v[216:219], v[22:25]
	v_mfma_f32_16x16x32_bf16 v[18:21], v[192:195], v[216:219], v[18:21]
	v_mfma_f32_16x16x32_bf16 v[6:9], v[172:175], v[224:227], v[6:9]
	v_mfma_f32_16x16x32_bf16 v[2:5], v[192:195], v[224:227], v[2:5]
	v_mfma_f32_16x16x32_bf16 v[54:57], v[188:191], v[204:207], v[54:57]
	v_mfma_f32_16x16x32_bf16 v[50:53], v[196:199], v[204:207], v[50:53]
	v_mfma_f32_16x16x32_bf16 v[38:41], v[188:191], v[212:215], v[38:41]
	v_mfma_f32_16x16x32_bf16 v[34:37], v[196:199], v[212:215], v[34:37]
	v_mfma_f32_16x16x32_bf16 v[22:25], v[188:191], v[220:223], v[22:25]
	v_mfma_f32_16x16x32_bf16 v[18:21], v[196:199], v[220:223], v[18:21]
	v_mfma_f32_16x16x32_bf16 v[6:9], v[188:191], v[228:231], v[6:9]
	v_mfma_f32_16x16x32_bf16 v[2:5], v[196:199], v[228:231], v[2:5]
	s_barrier
	s_add_u32 s44, s44, 0x100
	s_addc_u32 s45, s45, 0
	s_cmp_ge_i32 s41, s40
	s_cbranch_scc0 .LBB0_824
	s_branch .LBB0_826

.LBB0_828:
	ds_read_b128 v[158:161], v185
	ds_read_b128 v[162:165], v185 offset:1024
	ds_read_b128 v[166:169], v185 offset:2048
	ds_read_b128 v[170:173], v185 offset:3072
	ds_read_b128 v[174:177], v186
	ds_read_b128 v[190:193], v186 offset:1024
	ds_read_b128 v[194:197], v186 offset:2048
	ds_read_b128 v[198:201], v186 offset:3072
	s_add_i32 s42, s40, 1
	s_ashr_i32 s43, s42, 31
	s_lshl_b64 s[44:45], s[42:43], 7
	s_add_i32 s42, s40, 2
	s_add_u32 s43, s38, s0
	s_addc_u32 s41, s39, s1
	s_add_u32 s60, s36, s0
	s_addc_u32 s61, s37, s1
	s_cmp_eq_u32 s52, s40
	s_cselect_b32 s41, s13, s41
	s_cselect_b32 s40, s12, s43
	s_cselect_b32 s61, s35, s61
	s_cselect_b32 s60, s34, s60
	s_add_u32 s43, s38, s44
	s_addc_u32 s45, s39, s45
	s_add_u32 s44, s43, s8
	s_addc_u32 s45, s45, s9
	v_lshl_add_u64 v[182:183], s[44:45], 0, v[136:137]
	s_add_i32 m0, s5, 0xc000
	ds_read_b128 v[202:205], v187
	ds_read_b128 v[206:209], v187 offset:1024
	ds_read_b128 v[210:213], v187 offset:2048
	ds_read_b128 v[214:217], v187 offset:3072
	ds_read_b128 v[218:221], v187 offset:4096
	ds_read_b128 v[222:225], v187 offset:5120
	ds_read_b128 v[226:229], v187 offset:6144
	ds_read_b128 v[230:233], v187 offset:7168
	global_load_lds_dwordx4 v[182:183], off
	v_lshl_add_u64 v[182:183], s[44:45], 0, v[132:133]
	s_add_i32 m0, s5, 0xe000
	s_nop 0
	global_load_lds_dwordx4 v[182:183], off
	s_waitcnt vmcnt(8)
	s_waitcnt lgkmcnt(0)
	s_barrier
	s_waitcnt lgkmcnt(0)
	v_mfma_f32_16x16x32_bf16 v[70:73], v[158:161], v[202:205], v[70:73]
	v_mfma_f32_16x16x32_bf16 v[66:69], v[166:169], v[202:205], v[66:69]
	v_mfma_f32_16x16x32_bf16 v[86:89], v[158:161], v[210:213], v[86:89]
	v_mfma_f32_16x16x32_bf16 v[94:97], v[166:169], v[210:213], v[94:97]
	v_mfma_f32_16x16x32_bf16 v[110:113], v[158:161], v[218:221], v[110:113]
	v_mfma_f32_16x16x32_bf16 v[114:117], v[166:169], v[218:221], v[114:117]
	v_mfma_f32_16x16x32_bf16 v[126:129], v[158:161], v[226:229], v[126:129]
	v_mfma_f32_16x16x32_bf16 v[102:105], v[166:169], v[226:229], v[102:105]
	v_mfma_f32_16x16x32_bf16 v[70:73], v[162:165], v[206:209], v[70:73]
	v_mfma_f32_16x16x32_bf16 v[66:69], v[170:173], v[206:209], v[66:69]
	v_mfma_f32_16x16x32_bf16 v[86:89], v[162:165], v[214:217], v[86:89]
	v_mfma_f32_16x16x32_bf16 v[94:97], v[170:173], v[214:217], v[94:97]
	v_mfma_f32_16x16x32_bf16 v[110:113], v[162:165], v[222:225], v[110:113]
	v_mfma_f32_16x16x32_bf16 v[114:117], v[170:173], v[222:225], v[114:117]
	v_mfma_f32_16x16x32_bf16 v[126:129], v[162:165], v[230:233], v[126:129]
	v_mfma_f32_16x16x32_bf16 v[102:105], v[170:173], v[230:233], v[102:105]
	v_mfma_f32_16x16x32_bf16 v[74:77], v[174:177], v[202:205], v[74:77]
	v_mfma_f32_16x16x32_bf16 v[82:85], v[194:197], v[202:205], v[82:85]
	v_mfma_f32_16x16x32_bf16 v[98:101], v[174:177], v[210:213], v[98:101]
	v_mfma_f32_16x16x32_bf16 v[106:109], v[194:197], v[210:213], v[106:109]
	v_mfma_f32_16x16x32_bf16 v[118:121], v[174:177], v[218:221], v[118:121]
	v_mfma_f32_16x16x32_bf16 v[122:125], v[194:197], v[218:221], v[122:125]
	v_mfma_f32_16x16x32_bf16 v[90:93], v[174:177], v[226:229], v[90:93]
	v_mfma_f32_16x16x32_bf16 v[78:81], v[194:197], v[226:229], v[78:81]
	v_mfma_f32_16x16x32_bf16 v[74:77], v[190:193], v[206:209], v[74:77]
	v_mfma_f32_16x16x32_bf16 v[82:85], v[198:201], v[206:209], v[82:85]
	v_mfma_f32_16x16x32_bf16 v[98:101], v[190:193], v[214:217], v[98:101]
	v_mfma_f32_16x16x32_bf16 v[106:109], v[198:201], v[214:217], v[106:109]
	v_mfma_f32_16x16x32_bf16 v[118:121], v[190:193], v[222:225], v[118:121]
	v_mfma_f32_16x16x32_bf16 v[122:125], v[198:201], v[222:225], v[122:125]
	v_mfma_f32_16x16x32_bf16 v[90:93], v[190:193], v[230:233], v[90:93]
	v_mfma_f32_16x16x32_bf16 v[78:81], v[198:201], v[230:233], v[78:81]
	s_barrier
	s_add_i32 s43, s57, s4
	v_lshl_add_u64 v[182:183], s[60:61], 0, v[134:135]
	s_mov_b32 m0, s43
	ds_read_b128 v[202:205], v187 offset:16384
	ds_read_b128 v[206:209], v187 offset:17408
	ds_read_b128 v[210:213], v187 offset:18432
	ds_read_b128 v[214:217], v187 offset:19456
	ds_read_b128 v[218:221], v187 offset:20480
	ds_read_b128 v[222:225], v187 offset:21504
	ds_read_b128 v[226:229], v187 offset:22528
	ds_read_b128 v[230:233], v187 offset:23552
	global_load_lds_dwordx4 v[182:183], off
	s_add_i32 m0, s43, 0x2000
	s_add_u32 s44, s60, s8
	v_lshl_add_u64 v[234:235], s[60:61], 0, v[130:131]
	s_addc_u32 s45, s61, s9
	s_add_i32 s43, s58, s4
	global_load_lds_dwordx4 v[234:235], off
	v_lshl_add_u64 v[236:237], s[44:45], 0, v[134:135]
	s_mov_b32 m0, s43
	v_lshl_add_u64 v[238:239], s[44:45], 0, v[130:131]
	global_load_lds_dwordx4 v[236:237], off
	s_add_i32 m0, s43, 0x2000
	v_lshl_add_u64 v[240:241], s[40:41], 0, v[136:137]
	global_load_lds_dwordx4 v[238:239], off
	s_mov_b32 m0, s5
	v_lshl_add_u64 v[242:243], s[40:41], 0, v[132:133]
	global_load_lds_dwordx4 v[240:241], off
	s_mov_b32 m0, s46
	s_nop 0
	global_load_lds_dwordx4 v[242:243], off
	s_waitcnt vmcnt(8)
	s_waitcnt lgkmcnt(0)
	s_barrier
	s_waitcnt lgkmcnt(0)
	v_mfma_f32_16x16x32_bf16 v[62:65], v[158:161], v[202:205], v[62:65]
	v_mfma_f32_16x16x32_bf16 v[58:61], v[166:169], v[202:205], v[58:61]
	v_mfma_f32_16x16x32_bf16 v[46:49], v[158:161], v[210:213], v[46:49]
	v_mfma_f32_16x16x32_bf16 v[42:45], v[166:169], v[210:213], v[42:45]
	v_mfma_f32_16x16x32_bf16 v[30:33], v[158:161], v[218:221], v[30:33]
	v_mfma_f32_16x16x32_bf16 v[26:29], v[166:169], v[218:221], v[26:29]
	v_mfma_f32_16x16x32_bf16 v[14:17], v[158:161], v[226:229], v[14:17]
	v_mfma_f32_16x16x32_bf16 v[10:13], v[166:169], v[226:229], v[10:13]
	v_mfma_f32_16x16x32_bf16 v[62:65], v[162:165], v[206:209], v[62:65]
	v_mfma_f32_16x16x32_bf16 v[58:61], v[170:173], v[206:209], v[58:61]
	v_mfma_f32_16x16x32_bf16 v[46:49], v[162:165], v[214:217], v[46:49]
	v_mfma_f32_16x16x32_bf16 v[42:45], v[170:173], v[214:217], v[42:45]
	v_mfma_f32_16x16x32_bf16 v[30:33], v[162:165], v[222:225], v[30:33]
	v_mfma_f32_16x16x32_bf16 v[26:29], v[170:173], v[222:225], v[26:29]
	v_mfma_f32_16x16x32_bf16 v[14:17], v[162:165], v[230:233], v[14:17]
	v_mfma_f32_16x16x32_bf16 v[10:13], v[170:173], v[230:233], v[10:13]
	v_mfma_f32_16x16x32_bf16 v[54:57], v[174:177], v[202:205], v[54:57]
	v_mfma_f32_16x16x32_bf16 v[50:53], v[194:197], v[202:205], v[50:53]
	v_mfma_f32_16x16x32_bf16 v[38:41], v[174:177], v[210:213], v[38:41]
	v_mfma_f32_16x16x32_bf16 v[34:37], v[194:197], v[210:213], v[34:37]
	v_mfma_f32_16x16x32_bf16 v[22:25], v[174:177], v[218:221], v[22:25]
	v_mfma_f32_16x16x32_bf16 v[18:21], v[194:197], v[218:221], v[18:21]
	v_mfma_f32_16x16x32_bf16 v[6:9], v[174:177], v[226:229], v[6:9]
	v_mfma_f32_16x16x32_bf16 v[2:5], v[194:197], v[226:229], v[2:5]
	v_mfma_f32_16x16x32_bf16 v[54:57], v[190:193], v[206:209], v[54:57]
	v_mfma_f32_16x16x32_bf16 v[50:53], v[198:201], v[206:209], v[50:53]
	v_mfma_f32_16x16x32_bf16 v[38:41], v[190:193], v[214:217], v[38:41]
	v_mfma_f32_16x16x32_bf16 v[34:37], v[198:201], v[214:217], v[34:37]
	v_mfma_f32_16x16x32_bf16 v[22:25], v[190:193], v[222:225], v[22:25]
	v_mfma_f32_16x16x32_bf16 v[18:21], v[198:201], v[222:225], v[18:21]
	v_mfma_f32_16x16x32_bf16 v[6:9], v[190:193], v[230:233], v[6:9]
	v_mfma_f32_16x16x32_bf16 v[2:5], v[198:201], v[230:233], v[2:5]
	s_barrier
	s_add_i32 s43, 0, 0x18000
	v_add_u32_e32 v138, s43, v181
	s_add_i32 s44, 0, 0x1c000
	ds_read_b128 v[158:161], v138
	ds_read_b128 v[162:165], v138 offset:1024
	ds_read_b128 v[166:169], v138 offset:2048
	ds_read_b128 v[170:173], v138 offset:3072
	v_add_u32_e32 v138, s44, v181
	ds_read_b128 v[174:177], v138
	ds_read_b128 v[190:193], v138 offset:1024
	ds_read_b128 v[194:197], v138 offset:2048
	ds_read_b128 v[198:201], v138 offset:3072
	s_add_u32 s40, s40, s8
	s_addc_u32 s41, s41, s9
	s_mov_b32 m0, s47
	v_lshl_add_u64 v[244:245], s[40:41], 0, v[136:137]
	ds_read_b128 v[202:205], v187 offset:32768
	ds_read_b128 v[206:209], v187 offset:33792
	ds_read_b128 v[210:213], v187 offset:34816
	ds_read_b128 v[214:217], v187 offset:35840
	ds_read_b128 v[218:221], v187 offset:36864
	ds_read_b128 v[222:225], v187 offset:37888
	ds_read_b128 v[226:229], v187 offset:38912
	ds_read_b128 v[230:233], v187 offset:39936
	global_load_lds_dwordx4 v[244:245], off
	v_lshl_add_u64 v[244:245], s[40:41], 0, v[132:133]
	s_mov_b32 m0, s48
	s_nop 0
	global_load_lds_dwordx4 v[244:245], off
	s_waitcnt vmcnt(8)
	s_waitcnt lgkmcnt(0)
	s_barrier
	s_waitcnt lgkmcnt(0)
	v_mfma_f32_16x16x32_bf16 v[70:73], v[158:161], v[202:205], v[70:73]
	v_mfma_f32_16x16x32_bf16 v[66:69], v[166:169], v[202:205], v[66:69]
	v_mfma_f32_16x16x32_bf16 v[86:89], v[158:161], v[210:213], v[86:89]
	v_mfma_f32_16x16x32_bf16 v[94:97], v[166:169], v[210:213], v[94:97]
	v_mfma_f32_16x16x32_bf16 v[110:113], v[158:161], v[218:221], v[110:113]
	v_mfma_f32_16x16x32_bf16 v[114:117], v[166:169], v[218:221], v[114:117]
	v_mfma_f32_16x16x32_bf16 v[126:129], v[158:161], v[226:229], v[126:129]
	v_mfma_f32_16x16x32_bf16 v[102:105], v[166:169], v[226:229], v[102:105]
	v_mfma_f32_16x16x32_bf16 v[70:73], v[162:165], v[206:209], v[70:73]
	v_mfma_f32_16x16x32_bf16 v[66:69], v[170:173], v[206:209], v[66:69]
	v_mfma_f32_16x16x32_bf16 v[86:89], v[162:165], v[214:217], v[86:89]
	v_mfma_f32_16x16x32_bf16 v[94:97], v[170:173], v[214:217], v[94:97]
	v_mfma_f32_16x16x32_bf16 v[110:113], v[162:165], v[222:225], v[110:113]
	v_mfma_f32_16x16x32_bf16 v[114:117], v[170:173], v[222:225], v[114:117]
	v_mfma_f32_16x16x32_bf16 v[126:129], v[162:165], v[230:233], v[126:129]
	v_mfma_f32_16x16x32_bf16 v[102:105], v[170:173], v[230:233], v[102:105]
	v_mfma_f32_16x16x32_bf16 v[74:77], v[174:177], v[202:205], v[74:77]
	v_mfma_f32_16x16x32_bf16 v[82:85], v[194:197], v[202:205], v[82:85]
	v_mfma_f32_16x16x32_bf16 v[98:101], v[174:177], v[210:213], v[98:101]
	v_mfma_f32_16x16x32_bf16 v[106:109], v[194:197], v[210:213], v[106:109]
	v_mfma_f32_16x16x32_bf16 v[118:121], v[174:177], v[218:221], v[118:121]
	v_mfma_f32_16x16x32_bf16 v[122:125], v[194:197], v[218:221], v[122:125]
	v_mfma_f32_16x16x32_bf16 v[90:93], v[174:177], v[226:229], v[90:93]
	v_mfma_f32_16x16x32_bf16 v[78:81], v[194:197], v[226:229], v[78:81]
	v_mfma_f32_16x16x32_bf16 v[74:77], v[190:193], v[206:209], v[74:77]
	v_mfma_f32_16x16x32_bf16 v[82:85], v[198:201], v[206:209], v[82:85]
	v_mfma_f32_16x16x32_bf16 v[98:101], v[190:193], v[214:217], v[98:101]
	v_mfma_f32_16x16x32_bf16 v[106:109], v[198:201], v[214:217], v[106:109]
	v_mfma_f32_16x16x32_bf16 v[118:121], v[190:193], v[222:225], v[118:121]
	v_mfma_f32_16x16x32_bf16 v[122:125], v[198:201], v[222:225], v[122:125]
	v_mfma_f32_16x16x32_bf16 v[90:93], v[190:193], v[230:233], v[90:93]
	v_mfma_f32_16x16x32_bf16 v[78:81], v[198:201], v[230:233], v[78:81]
	s_barrier
	s_add_i32 s40, s43, s4
	v_lshl_add_u64 v[182:183], v[182:183], 0, s[22:23]
	s_mov_b32 m0, s40
	ds_read_b128 v[202:205], v187 offset:49152
	ds_read_b128 v[206:209], v187 offset:50176
	ds_read_b128 v[210:213], v187 offset:51200
	ds_read_b128 v[214:217], v187 offset:52224
	ds_read_b128 v[218:221], v187 offset:53248
	ds_read_b128 v[222:225], v187 offset:54272
	ds_read_b128 v[226:229], v187 offset:55296
	ds_read_b128 v[230:233], v187 offset:56320
	global_load_lds_dwordx4 v[182:183], off
	v_lshl_add_u64 v[182:183], v[234:235], 0, s[22:23]
	s_add_i32 m0, s40, 0x2000
	s_add_i32 s40, s44, s4
	global_load_lds_dwordx4 v[182:183], off
	v_lshl_add_u64 v[182:183], v[236:237], 0, s[22:23]
	s_mov_b32 m0, s40
	s_nop 0
	global_load_lds_dwordx4 v[182:183], off
	v_lshl_add_u64 v[182:183], v[238:239], 0, s[22:23]
	s_add_i32 m0, s40, 0x2000
	s_nop 0
	global_load_lds_dwordx4 v[182:183], off
	v_lshl_add_u64 v[182:183], v[240:241], 0, s[22:23]
	s_mov_b32 m0, s49
	s_nop 0
	global_load_lds_dwordx4 v[182:183], off
	v_lshl_add_u64 v[182:183], v[242:243], 0, s[22:23]
	s_mov_b32 m0, s50
	s_nop 0
	global_load_lds_dwordx4 v[182:183], off
	s_waitcnt vmcnt(8)
	s_waitcnt lgkmcnt(0)
	s_barrier
	s_waitcnt lgkmcnt(0)
	v_mfma_f32_16x16x32_bf16 v[62:65], v[158:161], v[202:205], v[62:65]
	v_mfma_f32_16x16x32_bf16 v[58:61], v[166:169], v[202:205], v[58:61]
	v_mfma_f32_16x16x32_bf16 v[46:49], v[158:161], v[210:213], v[46:49]
	v_mfma_f32_16x16x32_bf16 v[42:45], v[166:169], v[210:213], v[42:45]
	v_mfma_f32_16x16x32_bf16 v[30:33], v[158:161], v[218:221], v[30:33]
	v_mfma_f32_16x16x32_bf16 v[26:29], v[166:169], v[218:221], v[26:29]
	v_mfma_f32_16x16x32_bf16 v[14:17], v[158:161], v[226:229], v[14:17]
	v_mfma_f32_16x16x32_bf16 v[10:13], v[166:169], v[226:229], v[10:13]
	v_mfma_f32_16x16x32_bf16 v[62:65], v[162:165], v[206:209], v[62:65]
	v_mfma_f32_16x16x32_bf16 v[58:61], v[170:173], v[206:209], v[58:61]
	v_mfma_f32_16x16x32_bf16 v[46:49], v[162:165], v[214:217], v[46:49]
	v_mfma_f32_16x16x32_bf16 v[42:45], v[170:173], v[214:217], v[42:45]
	v_mfma_f32_16x16x32_bf16 v[30:33], v[162:165], v[222:225], v[30:33]
	v_mfma_f32_16x16x32_bf16 v[26:29], v[170:173], v[222:225], v[26:29]
	v_mfma_f32_16x16x32_bf16 v[14:17], v[162:165], v[230:233], v[14:17]
	v_mfma_f32_16x16x32_bf16 v[10:13], v[170:173], v[230:233], v[10:13]
	v_mfma_f32_16x16x32_bf16 v[54:57], v[174:177], v[202:205], v[54:57]
	v_mfma_f32_16x16x32_bf16 v[50:53], v[194:197], v[202:205], v[50:53]
	v_mfma_f32_16x16x32_bf16 v[38:41], v[174:177], v[210:213], v[38:41]
	v_mfma_f32_16x16x32_bf16 v[34:37], v[194:197], v[210:213], v[34:37]
	v_mfma_f32_16x16x32_bf16 v[22:25], v[174:177], v[218:221], v[22:25]
	v_mfma_f32_16x16x32_bf16 v[18:21], v[194:197], v[218:221], v[18:21]
	v_mfma_f32_16x16x32_bf16 v[6:9], v[174:177], v[226:229], v[6:9]
	v_mfma_f32_16x16x32_bf16 v[2:5], v[194:197], v[226:229], v[2:5]
	v_mfma_f32_16x16x32_bf16 v[54:57], v[190:193], v[206:209], v[54:57]
	v_mfma_f32_16x16x32_bf16 v[50:53], v[198:201], v[206:209], v[50:53]
	v_mfma_f32_16x16x32_bf16 v[38:41], v[190:193], v[214:217], v[38:41]
	v_mfma_f32_16x16x32_bf16 v[34:37], v[198:201], v[214:217], v[34:37]
	v_mfma_f32_16x16x32_bf16 v[22:25], v[190:193], v[222:225], v[22:25]
	v_mfma_f32_16x16x32_bf16 v[18:21], v[198:201], v[222:225], v[18:21]
	v_mfma_f32_16x16x32_bf16 v[6:9], v[190:193], v[230:233], v[6:9]
	v_mfma_f32_16x16x32_bf16 v[2:5], v[198:201], v[230:233], v[2:5]
	s_barrier
	s_add_u32 s0, s0, 0x100
	s_addc_u32 s1, s1, 0
	s_cmp_ge_i32 s42, s51
	s_mov_b32 s40, s42
	s_cbranch_scc0 .LBB0_828

.LBB0_834:
	s_setprio 0
	s_waitcnt vmcnt(0)
	s_barrier
	s_and_saveexec_b64 s[6:7], s[80:81]
	s_cbranch_execz .LBB0_849
	s_add_i32 s0, 0, 0x20164
	v_mov_b32_e32 v2, s0
	v_readlane_b32 s0, v246, 2
	v_mov_b32_e32 v3, 0x3000
	v_readlane_b32 s1, v246, 3
	ds_read_b32 v2, v2
	s_add_u32 s10, s0, 0x3200
	s_addc_u32 s11, s1, 0
	s_nop 1
	global_load_dword v3, v3, s[0:1] offset:512 sc1
	s_waitcnt vmcnt(0) lgkmcnt(0)
	v_cmp_ge_u32_e32 vcc, v3, v2
	s_cbranch_vccnz .LBB0_849
	v_readlane_b32 s0, v246, 2
	v_readlane_b32 s1, v246, 3
	s_add_u32 s8, s0, 0x4200
	s_addc_u32 s9, s1, 0
	s_mov_b32 s0, 1
	v_mov_b32_e32 v3, 0
	s_branch .LBB0_838

.LBB0_897:
	s_or_b64 exec, exec, s[6:7]
	v_readlane_b32 s0, v246, 2
	v_readlane_b32 s1, v246, 3
	s_add_u32 s2, s0, 0x7500000
	s_addc_u32 s3, s1, 0
	v_lshrrev_b32_e32 v3, 1, v0
	v_lshrrev_b32_e32 v4, 5, v0
	s_add_u32 s4, s0, 0x1100000
	v_lshlrev_b32_e32 v1, 4, v0
	v_and_b32_e32 v2, 32, v0
	v_and_b32_e32 v3, 24, v3
	v_and_b32_e32 v4, 4, v4
	v_bfe_u32 v5, v0, 2, 2
	s_addc_u32 s5, s1, 0
	s_ashr_i32 s36, s86, 1
	v_bfe_u32 v12, v0, 2, 4
	v_bitop3_b32 v10, v1, v2, 48 bitop3:0x6c
	v_and_b32_e32 v11, 64, v0
	v_or3_b32 v3, v4, v5, v3
	v_lshrrev_b32_e32 v4, 3, v0
	v_or_b32_e32 v13, 0x2000, v1
	s_and_b32 s14, s36, -2
	v_readfirstlane_b32 s0, v0
	v_or_b32_e32 v2, v10, v11
	v_and_or_b32 v5, v4, 48, v12
	v_and_or_b32 v4, v4, 32, v3
	v_lshrrev_b32_e32 v1, 7, v13
	s_movk_i32 s1, 0x70
	s_and_b32 s37, s86, 3
	s_lshr_b32 s7, s0, 6
	v_lshl_or_b32 v184, v4, 11, v2
	v_and_or_b32 v4, v1, s1, v12
	s_movk_i32 s1, 0x60
	s_ashr_i32 s15, s14, 31
	v_and_or_b32 v1, v1, s1, v3
	s_lshr_b32 s6, s0, 8
	s_lshl_b32 s38, s7, 10
	s_lshl_b64 s[10:11], s[14:15], 19
	s_lshl_b32 s1, s37, 19
	s_add_u32 s8, s4, s1
	s_addc_u32 s9, s5, 0
	s_add_i32 s39, s38, 0
	s_add_i32 m0, s39, 0x10000
	s_barrier
	global_load_lds_dwordx4 v184, s[8:9]
	s_add_i32 m0, s39, 0x12000
	v_lshl_or_b32 v188, v1, 11, v2
	s_add_u32 s12, s8, 0x40000
	global_load_lds_dwordx4 v188, s[8:9]
	s_addc_u32 s13, s9, 0
	s_add_i32 m0, s39, 0x14000
	v_lshl_or_b32 v182, v5, 11, v2
	global_load_lds_dwordx4 v184, s[12:13]
	s_add_i32 m0, s39, 0x16000
	s_add_u32 s10, s2, s10
	s_addc_u32 s11, s3, s11
	s_add_i32 s40, s39, 0x2000
	global_load_lds_dwordx4 v188, s[12:13]
	s_mov_b32 m0, s39
	s_add_u32 s12, s10, 0x40000
	v_lshl_or_b32 v186, v4, 11, v2
	global_load_lds_dwordx4 v182, s[10:11]
	s_mov_b32 m0, s40
	s_addc_u32 s13, s11, 0
	s_add_i32 s41, s39, 0x4000
	global_load_lds_dwordx4 v186, s[10:11]
	s_mov_b32 m0, s41
	s_add_i32 s42, s39, 0x6000
	global_load_lds_dwordx4 v182, s[12:13]
	s_mov_b32 m0, s42
	v_mov_b32_e32 v185, 0
	global_load_lds_dwordx4 v186, s[12:13]
	v_readlane_b32 s12, v246, 0
	v_readlane_b32 s13, v246, 1
	s_load_dwordx2 s[12:13], s[12:13], 0x0
	v_mov_b32_e32 v189, v185
	v_mov_b32_e32 v183, v185
	v_mov_b32_e32 v187, v185
	s_cmp_eq_u32 s6, 1
	s_mov_b32 s1, 4
	s_mov_b32 s15, 0
	v_lshl_add_u64 v[8:9], s[8:9], 0, v[184:185]
	v_lshl_add_u64 v[6:7], s[8:9], 0, v[188:189]
	v_lshl_add_u64 v[2:3], s[10:11], 0, v[182:183]
	s_cselect_b64 s[16:17], -1, 0
	s_cmp_lg_u32 s6, 1
	v_lshl_add_u64 v[4:5], s[10:11], 0, v[186:187]
	s_cbranch_scc1 .LBB0_899
	s_barrier
	s_setprio 1

.LBB0_903:
	ds_read_b128 v[130:133], v209
	ds_read_b128 v[134:137], v209 offset:1024
	ds_read_b128 v[138:141], v209 offset:2048
	ds_read_b128 v[142:145], v209 offset:3072
	ds_read_b128 v[146:149], v210
	ds_read_b128 v[150:153], v210 offset:1024
	ds_read_b128 v[154:157], v210 offset:2048
	ds_read_b128 v[158:161], v210 offset:3072
	s_add_u32 s30, s28, 0xfffc0080
	s_addc_u32 s31, s29, -1
	s_cmp_eq_u32 s55, 12
	s_cselect_b32 s35, s1, s31
	s_cselect_b32 s34, s50, s30
	s_cselect_b32 s31, s51, s54
	s_cselect_b32 s30, s52, s53
	v_lshl_add_u64 v[216:217], s[28:29], 0, v[190:191]
	s_add_i32 m0, s39, 0xc000
	ds_read_b128 v[162:165], v211
	ds_read_b128 v[166:169], v211 offset:1024
	ds_read_b128 v[170:173], v211 offset:2048
	ds_read_b128 v[174:177], v211 offset:3072
	ds_read_b128 v[194:197], v211 offset:4096
	ds_read_b128 v[198:201], v211 offset:5120
	ds_read_b128 v[202:205], v211 offset:6144
	ds_read_b128 v[212:215], v211 offset:7168
	global_load_lds_dwordx4 v[216:217], off
	v_lshl_add_u64 v[216:217], s[28:29], 0, v[192:193]
	s_add_i32 m0, s39, 0xe000
	s_nop 0
	global_load_lds_dwordx4 v[216:217], off
	s_waitcnt vmcnt(8)
	s_waitcnt lgkmcnt(0)
	s_barrier
	s_waitcnt lgkmcnt(0)
	v_mfma_f32_16x16x32_bf16 v[126:129], v[130:133], v[162:165], v[126:129]
	v_mfma_f32_16x16x32_bf16 v[122:125], v[138:141], v[162:165], v[122:125]
	v_mfma_f32_16x16x32_bf16 v[110:113], v[130:133], v[170:173], v[110:113]
	v_mfma_f32_16x16x32_bf16 v[106:109], v[138:141], v[170:173], v[106:109]
	v_mfma_f32_16x16x32_bf16 v[94:97], v[130:133], v[194:197], v[94:97]
	v_mfma_f32_16x16x32_bf16 v[90:93], v[138:141], v[194:197], v[90:93]
	v_mfma_f32_16x16x32_bf16 v[78:81], v[130:133], v[202:205], v[78:81]
	v_mfma_f32_16x16x32_bf16 v[74:77], v[138:141], v[202:205], v[74:77]
	v_mfma_f32_16x16x32_bf16 v[126:129], v[134:137], v[166:169], v[126:129]
	v_mfma_f32_16x16x32_bf16 v[122:125], v[142:145], v[166:169], v[122:125]
	v_mfma_f32_16x16x32_bf16 v[110:113], v[134:137], v[174:177], v[110:113]
	v_mfma_f32_16x16x32_bf16 v[106:109], v[142:145], v[174:177], v[106:109]
	v_mfma_f32_16x16x32_bf16 v[94:97], v[134:137], v[198:201], v[94:97]
	v_mfma_f32_16x16x32_bf16 v[90:93], v[142:145], v[198:201], v[90:93]
	v_mfma_f32_16x16x32_bf16 v[78:81], v[134:137], v[212:215], v[78:81]
	v_mfma_f32_16x16x32_bf16 v[74:77], v[142:145], v[212:215], v[74:77]
	v_mfma_f32_16x16x32_bf16 v[118:121], v[146:149], v[162:165], v[118:121]
	v_mfma_f32_16x16x32_bf16 v[114:117], v[154:157], v[162:165], v[114:117]
	v_mfma_f32_16x16x32_bf16 v[102:105], v[146:149], v[170:173], v[102:105]
	v_mfma_f32_16x16x32_bf16 v[98:101], v[154:157], v[170:173], v[98:101]
	v_mfma_f32_16x16x32_bf16 v[86:89], v[146:149], v[194:197], v[86:89]
	v_mfma_f32_16x16x32_bf16 v[82:85], v[154:157], v[194:197], v[82:85]
	v_mfma_f32_16x16x32_bf16 v[70:73], v[146:149], v[202:205], v[70:73]
	v_mfma_f32_16x16x32_bf16 v[66:69], v[154:157], v[202:205], v[66:69]
	v_mfma_f32_16x16x32_bf16 v[118:121], v[150:153], v[166:169], v[118:121]
	v_mfma_f32_16x16x32_bf16 v[114:117], v[158:161], v[166:169], v[114:117]
	v_mfma_f32_16x16x32_bf16 v[102:105], v[150:153], v[174:177], v[102:105]
	v_mfma_f32_16x16x32_bf16 v[98:101], v[158:161], v[174:177], v[98:101]
	v_mfma_f32_16x16x32_bf16 v[86:89], v[150:153], v[198:201], v[86:89]
	v_mfma_f32_16x16x32_bf16 v[82:85], v[158:161], v[198:201], v[82:85]
	v_mfma_f32_16x16x32_bf16 v[70:73], v[150:153], v[212:215], v[70:73]
	v_mfma_f32_16x16x32_bf16 v[66:69], v[158:161], v[212:215], v[66:69]
	s_barrier
	s_add_i32 s56, s48, s38
	v_lshl_add_u64 v[216:217], s[30:31], 0, v[184:185]
	s_mov_b32 m0, s56
	ds_read_b128 v[162:165], v211 offset:16384
	ds_read_b128 v[166:169], v211 offset:17408
	ds_read_b128 v[170:173], v211 offset:18432
	ds_read_b128 v[174:177], v211 offset:19456
	ds_read_b128 v[194:197], v211 offset:20480
	ds_read_b128 v[198:201], v211 offset:21504
	ds_read_b128 v[202:205], v211 offset:22528
	ds_read_b128 v[212:215], v211 offset:23552
	global_load_lds_dwordx4 v[216:217], off
	s_add_i32 m0, s56, 0x2000
	s_add_u32 s56, s30, 0x40000
	v_lshl_add_u64 v[218:219], s[30:31], 0, v[188:189]
	s_addc_u32 s57, s31, 0
	s_add_i32 s58, s49, s38
	global_load_lds_dwordx4 v[218:219], off
	v_lshl_add_u64 v[220:221], s[56:57], 0, v[184:185]
	s_mov_b32 m0, s58
	v_lshl_add_u64 v[222:223], s[34:35], 0, v[186:187]
	global_load_lds_dwordx4 v[220:221], off
	v_lshl_add_u64 v[220:221], s[56:57], 0, v[188:189]
	s_add_i32 m0, s58, 0x2000
	s_nop 0
	global_load_lds_dwordx4 v[220:221], off
	v_lshl_add_u64 v[220:221], s[34:35], 0, v[182:183]
	s_mov_b32 m0, s39
	s_nop 0
	global_load_lds_dwordx4 v[220:221], off
	s_mov_b32 m0, s40
	s_nop 0
	global_load_lds_dwordx4 v[222:223], off
	s_waitcnt vmcnt(8)
	s_waitcnt lgkmcnt(0)
	s_barrier
	s_waitcnt lgkmcnt(0)
	v_mfma_f32_16x16x32_bf16 v[62:65], v[130:133], v[162:165], v[62:65]
	v_mfma_f32_16x16x32_bf16 v[58:61], v[138:141], v[162:165], v[58:61]
	v_mfma_f32_16x16x32_bf16 v[46:49], v[130:133], v[170:173], v[46:49]
	v_mfma_f32_16x16x32_bf16 v[42:45], v[138:141], v[170:173], v[42:45]
	v_mfma_f32_16x16x32_bf16 v[30:33], v[130:133], v[194:197], v[30:33]
	v_mfma_f32_16x16x32_bf16 v[26:29], v[138:141], v[194:197], v[26:29]
	v_mfma_f32_16x16x32_bf16 v[14:17], v[130:133], v[202:205], v[14:17]
	v_mfma_f32_16x16x32_bf16 v[10:13], v[138:141], v[202:205], v[10:13]
	v_mfma_f32_16x16x32_bf16 v[62:65], v[134:137], v[166:169], v[62:65]
	v_mfma_f32_16x16x32_bf16 v[58:61], v[142:145], v[166:169], v[58:61]
	v_mfma_f32_16x16x32_bf16 v[46:49], v[134:137], v[174:177], v[46:49]
	v_mfma_f32_16x16x32_bf16 v[42:45], v[142:145], v[174:177], v[42:45]
	v_mfma_f32_16x16x32_bf16 v[30:33], v[134:137], v[198:201], v[30:33]
	v_mfma_f32_16x16x32_bf16 v[26:29], v[142:145], v[198:201], v[26:29]
	v_mfma_f32_16x16x32_bf16 v[14:17], v[134:137], v[212:215], v[14:17]
	v_mfma_f32_16x16x32_bf16 v[10:13], v[142:145], v[212:215], v[10:13]
	v_mfma_f32_16x16x32_bf16 v[54:57], v[146:149], v[162:165], v[54:57]
	v_mfma_f32_16x16x32_bf16 v[50:53], v[154:157], v[162:165], v[50:53]
	v_mfma_f32_16x16x32_bf16 v[38:41], v[146:149], v[170:173], v[38:41]
	v_mfma_f32_16x16x32_bf16 v[34:37], v[154:157], v[170:173], v[34:37]
	v_mfma_f32_16x16x32_bf16 v[22:25], v[146:149], v[194:197], v[22:25]
	v_mfma_f32_16x16x32_bf16 v[18:21], v[154:157], v[194:197], v[18:21]
	v_mfma_f32_16x16x32_bf16 v[6:9], v[146:149], v[202:205], v[6:9]
	v_mfma_f32_16x16x32_bf16 v[2:5], v[154:157], v[202:205], v[2:5]
	v_mfma_f32_16x16x32_bf16 v[54:57], v[150:153], v[166:169], v[54:57]
	v_mfma_f32_16x16x32_bf16 v[50:53], v[158:161], v[166:169], v[50:53]
	v_mfma_f32_16x16x32_bf16 v[38:41], v[150:153], v[174:177], v[38:41]
	v_mfma_f32_16x16x32_bf16 v[34:37], v[158:161], v[174:177], v[34:37]
	v_mfma_f32_16x16x32_bf16 v[22:25], v[150:153], v[198:201], v[22:25]
	v_mfma_f32_16x16x32_bf16 v[18:21], v[158:161], v[198:201], v[18:21]
	v_mfma_f32_16x16x32_bf16 v[6:9], v[150:153], v[212:215], v[6:9]
	v_mfma_f32_16x16x32_bf16 v[2:5], v[158:161], v[212:215], v[2:5]
	s_barrier
	s_add_i32 s56, 0, 0x18000
	s_add_i32 s57, 0, 0x1c000
	v_add_u32_e32 v142, s56, v207
	v_add_u32_e32 v158, s57, v207
	ds_read_b128 v[130:133], v142
	ds_read_b128 v[134:137], v142 offset:1024
	ds_read_b128 v[138:141], v142 offset:2048
	ds_read_b128 v[142:145], v142 offset:3072
	ds_read_b128 v[146:149], v158
	ds_read_b128 v[150:153], v158 offset:1024
	ds_read_b128 v[154:157], v158 offset:2048
	ds_read_b128 v[158:161], v158 offset:3072
	s_add_u32 s34, s34, 0x40000
	s_addc_u32 s35, s35, 0
	s_mov_b32 m0, s41
	v_lshl_add_u64 v[224:225], s[34:35], 0, v[182:183]
	ds_read_b128 v[162:165], v211 offset:32768
	ds_read_b128 v[166:169], v211 offset:33792
	ds_read_b128 v[170:173], v211 offset:34816
	ds_read_b128 v[174:177], v211 offset:35840
	ds_read_b128 v[194:197], v211 offset:36864
	ds_read_b128 v[198:201], v211 offset:37888
	ds_read_b128 v[202:205], v211 offset:38912
	ds_read_b128 v[212:215], v211 offset:39936
	global_load_lds_dwordx4 v[224:225], off
	v_lshl_add_u64 v[224:225], s[34:35], 0, v[186:187]
	s_mov_b32 m0, s42
	s_nop 0
	global_load_lds_dwordx4 v[224:225], off
	s_waitcnt vmcnt(8)
	s_waitcnt lgkmcnt(0)
	s_barrier
	s_waitcnt lgkmcnt(0)
	v_mfma_f32_16x16x32_bf16 v[126:129], v[130:133], v[162:165], v[126:129]
	v_mfma_f32_16x16x32_bf16 v[122:125], v[138:141], v[162:165], v[122:125]
	v_mfma_f32_16x16x32_bf16 v[110:113], v[130:133], v[170:173], v[110:113]
	v_mfma_f32_16x16x32_bf16 v[106:109], v[138:141], v[170:173], v[106:109]
	v_mfma_f32_16x16x32_bf16 v[94:97], v[130:133], v[194:197], v[94:97]
	v_mfma_f32_16x16x32_bf16 v[90:93], v[138:141], v[194:197], v[90:93]
	v_mfma_f32_16x16x32_bf16 v[78:81], v[130:133], v[202:205], v[78:81]
	v_mfma_f32_16x16x32_bf16 v[74:77], v[138:141], v[202:205], v[74:77]
	v_mfma_f32_16x16x32_bf16 v[126:129], v[134:137], v[166:169], v[126:129]
	v_mfma_f32_16x16x32_bf16 v[122:125], v[142:145], v[166:169], v[122:125]
	v_mfma_f32_16x16x32_bf16 v[110:113], v[134:137], v[174:177], v[110:113]
	v_mfma_f32_16x16x32_bf16 v[106:109], v[142:145], v[174:177], v[106:109]
	v_mfma_f32_16x16x32_bf16 v[94:97], v[134:137], v[198:201], v[94:97]
	v_mfma_f32_16x16x32_bf16 v[90:93], v[142:145], v[198:201], v[90:93]
	v_mfma_f32_16x16x32_bf16 v[78:81], v[134:137], v[212:215], v[78:81]
	v_mfma_f32_16x16x32_bf16 v[74:77], v[142:145], v[212:215], v[74:77]
	v_mfma_f32_16x16x32_bf16 v[118:121], v[146:149], v[162:165], v[118:121]
	v_mfma_f32_16x16x32_bf16 v[114:117], v[154:157], v[162:165], v[114:117]
	v_mfma_f32_16x16x32_bf16 v[102:105], v[146:149], v[170:173], v[102:105]
	v_mfma_f32_16x16x32_bf16 v[98:101], v[154:157], v[170:173], v[98:101]
	v_mfma_f32_16x16x32_bf16 v[86:89], v[146:149], v[194:197], v[86:89]
	v_mfma_f32_16x16x32_bf16 v[82:85], v[154:157], v[194:197], v[82:85]
	v_mfma_f32_16x16x32_bf16 v[70:73], v[146:149], v[202:205], v[70:73]
	v_mfma_f32_16x16x32_bf16 v[66:69], v[154:157], v[202:205], v[66:69]
	v_mfma_f32_16x16x32_bf16 v[118:121], v[150:153], v[166:169], v[118:121]
	v_mfma_f32_16x16x32_bf16 v[114:117], v[158:161], v[166:169], v[114:117]
	v_mfma_f32_16x16x32_bf16 v[102:105], v[150:153], v[174:177], v[102:105]
	v_mfma_f32_16x16x32_bf16 v[98:101], v[158:161], v[174:177], v[98:101]
	v_mfma_f32_16x16x32_bf16 v[86:89], v[150:153], v[198:201], v[86:89]
	v_mfma_f32_16x16x32_bf16 v[82:85], v[158:161], v[198:201], v[82:85]
	v_mfma_f32_16x16x32_bf16 v[70:73], v[150:153], v[212:215], v[70:73]
	v_mfma_f32_16x16x32_bf16 v[66:69], v[158:161], v[212:215], v[66:69]
	s_barrier
	s_add_i32 s34, s56, s38
	v_lshl_add_u64 v[216:217], v[216:217], 0, s[22:23]
	s_mov_b32 m0, s34
	ds_read_b128 v[162:165], v211 offset:49152
	ds_read_b128 v[166:169], v211 offset:50176
	ds_read_b128 v[170:173], v211 offset:51200
	ds_read_b128 v[174:177], v211 offset:52224
	ds_read_b128 v[194:197], v211 offset:53248
	ds_read_b128 v[198:201], v211 offset:54272
	ds_read_b128 v[202:205], v211 offset:55296
	ds_read_b128 v[212:215], v211 offset:56320
	global_load_lds_dwordx4 v[216:217], off
	s_add_i32 m0, s34, 0x2000
	s_add_u32 s30, s30, 0x40080
	v_lshl_add_u64 v[216:217], v[218:219], 0, s[22:23]
	s_addc_u32 s31, s31, 0
	s_add_i32 s34, s57, s38
	global_load_lds_dwordx4 v[216:217], off
	v_lshl_add_u64 v[216:217], s[30:31], 0, v[184:185]
	s_mov_b32 m0, s34
	s_nop 0
	global_load_lds_dwordx4 v[216:217], off
	v_lshl_add_u64 v[216:217], s[30:31], 0, v[188:189]
	s_add_i32 m0, s34, 0x2000
	s_nop 0
	global_load_lds_dwordx4 v[216:217], off
	v_lshl_add_u64 v[216:217], v[220:221], 0, s[22:23]
	s_mov_b32 m0, s44
	s_nop 0
	global_load_lds_dwordx4 v[216:217], off
	v_lshl_add_u64 v[216:217], v[222:223], 0, s[22:23]
	s_mov_b32 m0, s45
	s_nop 0
	global_load_lds_dwordx4 v[216:217], off
	s_waitcnt vmcnt(8)
	s_waitcnt lgkmcnt(0)
	s_barrier
	s_waitcnt lgkmcnt(0)
	v_mfma_f32_16x16x32_bf16 v[62:65], v[130:133], v[162:165], v[62:65]
	v_mfma_f32_16x16x32_bf16 v[58:61], v[138:141], v[162:165], v[58:61]
	v_mfma_f32_16x16x32_bf16 v[46:49], v[130:133], v[170:173], v[46:49]
	v_mfma_f32_16x16x32_bf16 v[42:45], v[138:141], v[170:173], v[42:45]
	v_mfma_f32_16x16x32_bf16 v[30:33], v[130:133], v[194:197], v[30:33]
	v_mfma_f32_16x16x32_bf16 v[26:29], v[138:141], v[194:197], v[26:29]
	v_mfma_f32_16x16x32_bf16 v[14:17], v[130:133], v[202:205], v[14:17]
	v_mfma_f32_16x16x32_bf16 v[10:13], v[138:141], v[202:205], v[10:13]
	v_mfma_f32_16x16x32_bf16 v[62:65], v[134:137], v[166:169], v[62:65]
	v_mfma_f32_16x16x32_bf16 v[58:61], v[142:145], v[166:169], v[58:61]
	v_mfma_f32_16x16x32_bf16 v[46:49], v[134:137], v[174:177], v[46:49]
	v_mfma_f32_16x16x32_bf16 v[42:45], v[142:145], v[174:177], v[42:45]
	v_mfma_f32_16x16x32_bf16 v[30:33], v[134:137], v[198:201], v[30:33]
	v_mfma_f32_16x16x32_bf16 v[26:29], v[142:145], v[198:201], v[26:29]
	v_mfma_f32_16x16x32_bf16 v[14:17], v[134:137], v[212:215], v[14:17]
	v_mfma_f32_16x16x32_bf16 v[10:13], v[142:145], v[212:215], v[10:13]
	v_mfma_f32_16x16x32_bf16 v[54:57], v[146:149], v[162:165], v[54:57]
	v_mfma_f32_16x16x32_bf16 v[50:53], v[154:157], v[162:165], v[50:53]
	v_mfma_f32_16x16x32_bf16 v[38:41], v[146:149], v[170:173], v[38:41]
	v_mfma_f32_16x16x32_bf16 v[34:37], v[154:157], v[170:173], v[34:37]
	v_mfma_f32_16x16x32_bf16 v[22:25], v[146:149], v[194:197], v[22:25]
	v_mfma_f32_16x16x32_bf16 v[18:21], v[154:157], v[194:197], v[18:21]
	v_mfma_f32_16x16x32_bf16 v[6:9], v[146:149], v[202:205], v[6:9]
	v_mfma_f32_16x16x32_bf16 v[2:5], v[154:157], v[202:205], v[2:5]
	v_mfma_f32_16x16x32_bf16 v[54:57], v[150:153], v[166:169], v[54:57]
	v_mfma_f32_16x16x32_bf16 v[50:53], v[158:161], v[166:169], v[50:53]
	v_mfma_f32_16x16x32_bf16 v[38:41], v[150:153], v[174:177], v[38:41]
	v_mfma_f32_16x16x32_bf16 v[34:37], v[158:161], v[174:177], v[34:37]
	v_mfma_f32_16x16x32_bf16 v[22:25], v[150:153], v[198:201], v[22:25]
	v_mfma_f32_16x16x32_bf16 v[18:21], v[158:161], v[198:201], v[18:21]
	v_mfma_f32_16x16x32_bf16 v[6:9], v[150:153], v[212:215], v[6:9]
	v_mfma_f32_16x16x32_bf16 v[2:5], v[158:161], v[212:215], v[2:5]
	s_barrier
	s_add_i32 s55, s55, 2
	s_add_u32 s28, s28, 0x100
	s_addc_u32 s29, s29, 0
	s_add_u32 s53, s53, 0x100
	s_addc_u32 s54, s54, 0
	s_cmp_gt_u32 s55, 13
	s_cbranch_scc0 .LBB0_903
	s_and_b64 vcc, exec, s[24:25]
	s_cbranch_vccz .LBB0_906
	s_barrier

.LBB0_925:
	s_setprio 0
	s_waitcnt vmcnt(0)
	s_barrier
	s_and_saveexec_b64 s[6:7], s[80:81]
	s_cbranch_execz .LBB0_940
	s_add_i32 s0, 0, 0x20164
	v_mov_b32_e32 v2, s0
	v_readlane_b32 s0, v246, 2
	s_waitcnt lgkmcnt(0)
	v_mov_b32_e32 v3, 0x3000
	v_readlane_b32 s1, v246, 3
	ds_read_b32 v2, v2
	s_add_u32 s10, s0, 0x3240
	s_addc_u32 s11, s1, 0
	s_nop 1
	global_load_dword v3, v3, s[0:1] offset:576 sc1
	buffer_inv sc1
	s_waitcnt vmcnt(0) lgkmcnt(0)
	v_cmp_ge_u32_e32 vcc, v3, v2
	s_cbranch_vccnz .LBB0_940
	v_readlane_b32 s0, v246, 2
	v_readlane_b32 s1, v246, 3
	s_add_u32 s8, s0, 0x4200
	s_addc_u32 s9, s1, 0
	s_mov_b32 s0, 1
	v_mov_b32_e32 v3, 0
	s_branch .LBB0_929

.LBB0_983:
	s_or_b64 exec, exec, s[6:7]
	v_readlane_b32 s98, v246, 2
	v_readlane_b32 s99, v246, 3
	s_ashr_i32 s100, s86, 1
	s_and_b32 s100, s100, -2
	s_lshl_b32 s100, s100, 14
	s_add_u32 s98, s98, s100
	s_addc_u32 s99, s99, 0
	s_add_u32 s98, s98, 0x1bb00000
	s_addc_u32 s99, s99, 0
	v_lshlrev_b32_e32 v130, 6, v0
	global_load_dwordx4 v[114:117], v130, s[98:99]
	global_load_dwordx4 v[118:121], v130, s[98:99] offset:16
	global_load_dwordx4 v[122:125], v130, s[98:99] offset:32
	global_load_dwordx4 v[126:129], v130, s[98:99] offset:48
	v_readlane_b32 s0, v246, 2
	v_readlane_b32 s1, v246, 3
	s_add_u32 s48, s0, 0xb600000
	s_addc_u32 s49, s1, 0
	v_lshrrev_b32_e32 v3, 1, v0
	v_lshrrev_b32_e32 v4, 5, v0
	s_add_u32 s50, s0, 0x1300000
	v_lshlrev_b32_e32 v1, 4, v0
	v_and_b32_e32 v2, 32, v0
	v_and_b32_e32 v3, 24, v3
	v_and_b32_e32 v4, 4, v4
	v_bfe_u32 v5, v0, 2, 2
	s_addc_u32 s51, s1, 0
	s_ashr_i32 s2, s86, 1
	v_bfe_u32 v12, v0, 2, 4
	v_bitop3_b32 v10, v1, v2, 48 bitop3:0x6c
	v_and_b32_e32 v11, 64, v0
	v_or3_b32 v3, v4, v5, v3
	v_lshrrev_b32_e32 v4, 3, v0
	v_or_b32_e32 v13, 0x2000, v1
	v_readfirstlane_b32 s0, v0
	v_or_b32_e32 v2, v10, v11
	v_and_or_b32 v5, v4, 48, v12
	v_and_or_b32 v4, v4, 32, v3
	v_lshrrev_b32_e32 v1, 7, v13
	s_movk_i32 s1, 0x70
	s_or_b32 s6, s2, 1
	s_and_b32 s52, s86, 3
	s_lshr_b32 s3, s0, 6
	v_lshl_or_b32 v184, v4, 11, v2
	v_and_or_b32 v4, v1, s1, v12
	s_movk_i32 s1, 0x60
	s_ashr_i32 s7, s6, 31
	v_and_or_b32 v1, v1, s1, v3
	s_lshr_b32 s1, s0, 8
	s_lshl_b32 s53, s3, 10
	s_lshl_b64 s[4:5], s[6:7], 19
	s_lshl_b32 s7, s52, 19
	s_add_u32 s10, s50, s7
	s_addc_u32 s11, s51, 0
	s_add_i32 s54, s53, 0
	s_add_i32 m0, s54, 0x10000
	v_lshl_or_b32 v188, v1, 11, v2
	global_load_lds_dwordx4 v184, s[10:11]
	s_add_i32 m0, s54, 0x12000
	s_add_u32 s8, s10, 0x40000
	global_load_lds_dwordx4 v188, s[10:11]
	s_addc_u32 s9, s11, 0
	s_add_i32 m0, s54, 0x14000
	v_lshl_or_b32 v182, v5, 11, v2
	global_load_lds_dwordx4 v184, s[8:9]
	s_add_i32 m0, s54, 0x16000
	v_lshl_or_b32 v186, v4, 11, v2
	global_load_lds_dwordx4 v188, s[8:9]
	s_add_u32 s8, s48, s4
	s_addc_u32 s9, s49, s5
	s_add_i32 s55, s54, 0x2000
	s_mov_b32 m0, s54
	s_add_u32 s4, s8, 0x40000
	global_load_lds_dwordx4 v182, s[8:9]
	s_mov_b32 m0, s55
	s_addc_u32 s5, s9, 0
	s_add_i32 s56, s54, 0x4000
	global_load_lds_dwordx4 v186, s[8:9]
	s_mov_b32 m0, s56
	s_add_i32 s57, s54, 0x6000
	global_load_lds_dwordx4 v182, s[4:5]
	s_mov_b32 m0, s57
	v_mov_b32_e32 v185, 0
	global_load_lds_dwordx4 v186, s[4:5]
	v_readlane_b32 s4, v246, 0
	v_readlane_b32 s5, v246, 1
	s_load_dwordx8 s[12:19], s[4:5], 0x10
	s_load_dwordx2 s[20:21], s[4:5], 0xa0
	v_mov_b32_e32 v189, v185
	v_mov_b32_e32 v183, v185
	v_mov_b32_e32 v187, v185
	s_cmp_eq_u32 s1, 1
	s_mov_b32 s23, 0
	v_lshl_add_u64 v[8:9], s[10:11], 0, v[184:185]
	v_lshl_add_u64 v[6:7], s[10:11], 0, v[188:189]
	v_lshl_add_u64 v[2:3], s[8:9], 0, v[182:183]
	s_cselect_b64 s[24:25], -1, 0
	s_cmp_lg_u32 s1, 1
	v_lshl_add_u64 v[4:5], s[8:9], 0, v[186:187]
	s_cbranch_scc1 .LBB0_985
	s_barrier
	s_setprio 1

.LBB0_991:
	ds_read_b128 v[66:69], v219
	ds_read_b128 v[70:73], v219 offset:1024
	ds_read_b128 v[86:89], v219 offset:2048
	ds_read_b128 v[106:109], v219 offset:3072
	ds_read_b128 v[146:149], v220
	ds_read_b128 v[150:153], v220 offset:1024
	ds_read_b128 v[154:157], v220 offset:2048
	ds_read_b128 v[158:161], v220 offset:3072
	s_add_u32 s10, s8, 0xfffc0080
	s_addc_u32 s11, s9, -1
	s_cmp_eq_u32 s22, 12
	s_cselect_b32 s45, s1, s11
	s_cselect_b32 s44, s2, s10
	s_cselect_b32 s11, s3, s7
	s_cselect_b32 s10, s4, s5
	s_add_i32 m0, s54, 0xc000
	ds_read_b128 v[162:165], v221
	ds_read_b128 v[166:169], v221 offset:1024
	ds_read_b128 v[170:173], v221 offset:2048
	ds_read_b128 v[174:177], v221 offset:3072
	ds_read_b128 v[196:199], v221 offset:4096
	ds_read_b128 v[200:203], v221 offset:5120
	ds_read_b128 v[204:207], v221 offset:6144
	ds_read_b128 v[208:211], v221 offset:7168
	global_load_lds_dwordx4 v192, s[8:9]
	s_add_i32 m0, s54, 0xe000
	s_nop 0
	global_load_lds_dwordx4 v194, s[8:9]
	s_waitcnt vmcnt(8)
	s_waitcnt lgkmcnt(0)
	s_barrier
	s_waitcnt lgkmcnt(0)
	v_mfma_f32_16x16x32_bf16 v[142:145], v[66:69], v[162:165], v[142:145]
	v_mfma_f32_16x16x32_bf16 v[134:137], v[86:89], v[162:165], v[134:137]
	v_mfma_f32_16x16x32_bf16 v[126:129], v[66:69], v[170:173], v[126:129]
	v_mfma_f32_16x16x32_bf16 v[122:125], v[86:89], v[170:173], v[122:125]
	v_mfma_f32_16x16x32_bf16 v[110:113], v[66:69], v[196:199], v[110:113]
	v_mfma_f32_16x16x32_bf16 v[102:105], v[86:89], v[196:199], v[102:105]
	v_mfma_f32_16x16x32_bf16 v[90:93], v[66:69], v[204:207], v[90:93]
	v_mfma_f32_16x16x32_bf16 v[82:85], v[86:89], v[204:207], v[82:85]
	v_mfma_f32_16x16x32_bf16 v[142:145], v[70:73], v[166:169], v[142:145]
	v_mfma_f32_16x16x32_bf16 v[134:137], v[106:109], v[166:169], v[134:137]
	v_mfma_f32_16x16x32_bf16 v[126:129], v[70:73], v[174:177], v[126:129]
	v_mfma_f32_16x16x32_bf16 v[122:125], v[106:109], v[174:177], v[122:125]
	v_mfma_f32_16x16x32_bf16 v[110:113], v[70:73], v[200:203], v[110:113]
	v_mfma_f32_16x16x32_bf16 v[102:105], v[106:109], v[200:203], v[102:105]
	v_mfma_f32_16x16x32_bf16 v[90:93], v[70:73], v[208:211], v[90:93]
	v_mfma_f32_16x16x32_bf16 v[82:85], v[106:109], v[208:211], v[82:85]
	v_mfma_f32_16x16x32_bf16 v[138:141], v[146:149], v[162:165], v[138:141]
	v_mfma_f32_16x16x32_bf16 v[130:133], v[154:157], v[162:165], v[130:133]
	v_mfma_f32_16x16x32_bf16 v[118:121], v[146:149], v[170:173], v[118:121]
	v_mfma_f32_16x16x32_bf16 v[114:117], v[154:157], v[170:173], v[114:117]
	v_mfma_f32_16x16x32_bf16 v[98:101], v[146:149], v[196:199], v[98:101]
	v_mfma_f32_16x16x32_bf16 v[94:97], v[154:157], v[196:199], v[94:97]
	v_mfma_f32_16x16x32_bf16 v[78:81], v[146:149], v[204:207], v[78:81]
	v_mfma_f32_16x16x32_bf16 v[74:77], v[154:157], v[204:207], v[74:77]
	v_mfma_f32_16x16x32_bf16 v[138:141], v[150:153], v[166:169], v[138:141]
	v_mfma_f32_16x16x32_bf16 v[130:133], v[158:161], v[166:169], v[130:133]
	v_mfma_f32_16x16x32_bf16 v[118:121], v[150:153], v[174:177], v[118:121]
	v_mfma_f32_16x16x32_bf16 v[114:117], v[158:161], v[174:177], v[114:117]
	v_mfma_f32_16x16x32_bf16 v[98:101], v[150:153], v[200:203], v[98:101]
	v_mfma_f32_16x16x32_bf16 v[94:97], v[158:161], v[200:203], v[94:97]
	v_mfma_f32_16x16x32_bf16 v[78:81], v[150:153], v[208:211], v[78:81]
	v_mfma_f32_16x16x32_bf16 v[74:77], v[158:161], v[208:211], v[74:77]
	s_barrier
	s_add_i32 s37, s62, s53
	s_mov_b32 m0, s37
	ds_read_b128 v[162:165], v221 offset:16384
	ds_read_b128 v[166:169], v221 offset:17408
	ds_read_b128 v[170:173], v221 offset:18432
	ds_read_b128 v[174:177], v221 offset:19456
	ds_read_b128 v[196:199], v221 offset:20480
	ds_read_b128 v[200:203], v221 offset:21504
	ds_read_b128 v[204:207], v221 offset:22528
	ds_read_b128 v[208:211], v221 offset:23552
	global_load_lds_dwordx4 v184, s[10:11]
	s_add_i32 m0, s37, 0x2000
	s_add_u32 s46, s10, 0x40000
	s_addc_u32 s47, s11, 0
	s_add_i32 s37, s63, s53
	global_load_lds_dwordx4 v188, s[10:11]
	s_mov_b32 m0, s37
	s_nop 0
	global_load_lds_dwordx4 v184, s[46:47]
	s_add_i32 m0, s37, 0x2000
	s_nop 0
	global_load_lds_dwordx4 v188, s[46:47]
	s_mov_b32 m0, s54
	s_nop 0
	global_load_lds_dwordx4 v182, s[44:45]
	s_mov_b32 m0, s55
	s_nop 0
	global_load_lds_dwordx4 v186, s[44:45]
	s_waitcnt vmcnt(8)
	s_waitcnt lgkmcnt(0)
	s_barrier
	s_waitcnt lgkmcnt(0)
	v_mfma_f32_16x16x32_bf16 v[62:65], v[66:69], v[162:165], v[62:65]
	v_mfma_f32_16x16x32_bf16 v[54:57], v[86:89], v[162:165], v[54:57]
	v_mfma_f32_16x16x32_bf16 v[46:49], v[66:69], v[170:173], v[46:49]
	v_mfma_f32_16x16x32_bf16 v[42:45], v[86:89], v[170:173], v[42:45]
	v_mfma_f32_16x16x32_bf16 v[30:33], v[66:69], v[196:199], v[30:33]
	v_mfma_f32_16x16x32_bf16 v[26:29], v[86:89], v[196:199], v[26:29]
	v_mfma_f32_16x16x32_bf16 v[14:17], v[66:69], v[204:207], v[14:17]
	v_mfma_f32_16x16x32_bf16 v[10:13], v[86:89], v[204:207], v[10:13]
	v_mfma_f32_16x16x32_bf16 v[62:65], v[70:73], v[166:169], v[62:65]
	v_mfma_f32_16x16x32_bf16 v[54:57], v[106:109], v[166:169], v[54:57]
	v_mfma_f32_16x16x32_bf16 v[46:49], v[70:73], v[174:177], v[46:49]
	v_mfma_f32_16x16x32_bf16 v[42:45], v[106:109], v[174:177], v[42:45]
	v_mfma_f32_16x16x32_bf16 v[30:33], v[70:73], v[200:203], v[30:33]
	v_mfma_f32_16x16x32_bf16 v[26:29], v[106:109], v[200:203], v[26:29]
	v_mfma_f32_16x16x32_bf16 v[14:17], v[70:73], v[208:211], v[14:17]
	v_mfma_f32_16x16x32_bf16 v[10:13], v[106:109], v[208:211], v[10:13]
	v_mfma_f32_16x16x32_bf16 v[58:61], v[146:149], v[162:165], v[58:61]
	v_mfma_f32_16x16x32_bf16 v[50:53], v[154:157], v[162:165], v[50:53]
	v_mfma_f32_16x16x32_bf16 v[38:41], v[146:149], v[170:173], v[38:41]
	v_mfma_f32_16x16x32_bf16 v[34:37], v[154:157], v[170:173], v[34:37]
	v_mfma_f32_16x16x32_bf16 v[22:25], v[146:149], v[196:199], v[22:25]
	v_mfma_f32_16x16x32_bf16 v[18:21], v[154:157], v[196:199], v[18:21]
	v_mfma_f32_16x16x32_bf16 v[6:9], v[146:149], v[204:207], v[6:9]
	v_mfma_f32_16x16x32_bf16 v[2:5], v[154:157], v[204:207], v[2:5]
	v_mfma_f32_16x16x32_bf16 v[58:61], v[150:153], v[166:169], v[58:61]
	v_mfma_f32_16x16x32_bf16 v[50:53], v[158:161], v[166:169], v[50:53]
	v_mfma_f32_16x16x32_bf16 v[38:41], v[150:153], v[174:177], v[38:41]
	v_mfma_f32_16x16x32_bf16 v[34:37], v[158:161], v[174:177], v[34:37]
	v_mfma_f32_16x16x32_bf16 v[22:25], v[150:153], v[200:203], v[22:25]
	v_mfma_f32_16x16x32_bf16 v[18:21], v[158:161], v[200:203], v[18:21]
	v_mfma_f32_16x16x32_bf16 v[6:9], v[150:153], v[208:211], v[6:9]
	v_mfma_f32_16x16x32_bf16 v[2:5], v[158:161], v[208:211], v[2:5]
	s_barrier
	s_add_i32 s37, 0, 0x18000
	s_add_i32 s39, 0, 0x1c000
	v_add_u32_e32 v106, s37, v213
	v_add_u32_e32 v158, s39, v213
	ds_read_b128 v[66:69], v106
	ds_read_b128 v[70:73], v106 offset:1024
	ds_read_b128 v[86:89], v106 offset:2048
	ds_read_b128 v[106:109], v106 offset:3072
	ds_read_b128 v[146:149], v158
	ds_read_b128 v[150:153], v158 offset:1024
	ds_read_b128 v[154:157], v158 offset:2048
	ds_read_b128 v[158:161], v158 offset:3072
	s_add_u32 s44, s44, 0x40000
	s_addc_u32 s45, s45, 0
	s_mov_b32 m0, s56
	ds_read_b128 v[162:165], v221 offset:32768
	ds_read_b128 v[166:169], v221 offset:33792
	ds_read_b128 v[170:173], v221 offset:34816
	ds_read_b128 v[174:177], v221 offset:35840
	ds_read_b128 v[196:199], v221 offset:36864
	ds_read_b128 v[200:203], v221 offset:37888
	ds_read_b128 v[204:207], v221 offset:38912
	ds_read_b128 v[208:211], v221 offset:39936
	global_load_lds_dwordx4 v182, s[44:45]
	s_mov_b32 m0, s57
	s_nop 0
	global_load_lds_dwordx4 v186, s[44:45]
	s_waitcnt vmcnt(8)
	s_waitcnt lgkmcnt(0)
	s_barrier
	s_waitcnt lgkmcnt(0)
	v_mfma_f32_16x16x32_bf16 v[142:145], v[66:69], v[162:165], v[142:145]
	v_mfma_f32_16x16x32_bf16 v[134:137], v[86:89], v[162:165], v[134:137]
	v_mfma_f32_16x16x32_bf16 v[126:129], v[66:69], v[170:173], v[126:129]
	v_mfma_f32_16x16x32_bf16 v[122:125], v[86:89], v[170:173], v[122:125]
	v_mfma_f32_16x16x32_bf16 v[110:113], v[66:69], v[196:199], v[110:113]
	v_mfma_f32_16x16x32_bf16 v[102:105], v[86:89], v[196:199], v[102:105]
	v_mfma_f32_16x16x32_bf16 v[90:93], v[66:69], v[204:207], v[90:93]
	v_mfma_f32_16x16x32_bf16 v[82:85], v[86:89], v[204:207], v[82:85]
	v_mfma_f32_16x16x32_bf16 v[142:145], v[70:73], v[166:169], v[142:145]
	v_mfma_f32_16x16x32_bf16 v[134:137], v[106:109], v[166:169], v[134:137]
	v_mfma_f32_16x16x32_bf16 v[126:129], v[70:73], v[174:177], v[126:129]
	v_mfma_f32_16x16x32_bf16 v[122:125], v[106:109], v[174:177], v[122:125]
	v_mfma_f32_16x16x32_bf16 v[110:113], v[70:73], v[200:203], v[110:113]
	v_mfma_f32_16x16x32_bf16 v[102:105], v[106:109], v[200:203], v[102:105]
	v_mfma_f32_16x16x32_bf16 v[90:93], v[70:73], v[208:211], v[90:93]
	v_mfma_f32_16x16x32_bf16 v[82:85], v[106:109], v[208:211], v[82:85]
	v_mfma_f32_16x16x32_bf16 v[138:141], v[146:149], v[162:165], v[138:141]
	v_mfma_f32_16x16x32_bf16 v[130:133], v[154:157], v[162:165], v[130:133]
	v_mfma_f32_16x16x32_bf16 v[118:121], v[146:149], v[170:173], v[118:121]
	v_mfma_f32_16x16x32_bf16 v[114:117], v[154:157], v[170:173], v[114:117]
	v_mfma_f32_16x16x32_bf16 v[98:101], v[146:149], v[196:199], v[98:101]
	v_mfma_f32_16x16x32_bf16 v[94:97], v[154:157], v[196:199], v[94:97]
	v_mfma_f32_16x16x32_bf16 v[78:81], v[146:149], v[204:207], v[78:81]
	v_mfma_f32_16x16x32_bf16 v[74:77], v[154:157], v[204:207], v[74:77]
	v_mfma_f32_16x16x32_bf16 v[138:141], v[150:153], v[166:169], v[138:141]
	v_mfma_f32_16x16x32_bf16 v[130:133], v[158:161], v[166:169], v[130:133]
	v_mfma_f32_16x16x32_bf16 v[118:121], v[150:153], v[174:177], v[118:121]
	v_mfma_f32_16x16x32_bf16 v[114:117], v[158:161], v[174:177], v[114:117]
	v_mfma_f32_16x16x32_bf16 v[98:101], v[150:153], v[200:203], v[98:101]
	v_mfma_f32_16x16x32_bf16 v[94:97], v[158:161], v[200:203], v[94:97]
	v_mfma_f32_16x16x32_bf16 v[78:81], v[150:153], v[208:211], v[78:81]
	v_mfma_f32_16x16x32_bf16 v[74:77], v[158:161], v[208:211], v[74:77]
	s_barrier
	s_add_i32 s37, s37, s53
	s_mov_b32 m0, s37
	ds_read_b128 v[162:165], v221 offset:49152
	ds_read_b128 v[166:169], v221 offset:50176
	ds_read_b128 v[170:173], v221 offset:51200
	ds_read_b128 v[174:177], v221 offset:52224
	ds_read_b128 v[196:199], v221 offset:53248
	ds_read_b128 v[200:203], v221 offset:54272
	ds_read_b128 v[204:207], v221 offset:55296
	ds_read_b128 v[208:211], v221 offset:56320
	s_add_u32 s98, s10, 0x80
	s_addc_u32 s99, s11, 0
	global_load_lds_dwordx4 v184, s[98:99]
	s_add_i32 m0, s37, 0x2000
	s_add_u32 s10, s10, 0x40080
	s_addc_u32 s11, s11, 0
	s_add_i32 s37, s39, s53
	global_load_lds_dwordx4 v188, s[98:99]
	s_mov_b32 m0, s37
	s_nop 0
	global_load_lds_dwordx4 v184, s[10:11]
	s_add_i32 m0, s37, 0x2000
	s_nop 0
	global_load_lds_dwordx4 v188, s[10:11]
	s_add_u32 s98, s44, 0xfffc0080
	s_addc_u32 s99, s45, -1
	s_mov_b32 m0, s60
	s_nop 0
	global_load_lds_dwordx4 v182, s[98:99]
	s_mov_b32 m0, s61
	s_nop 0
	global_load_lds_dwordx4 v186, s[98:99]
	s_waitcnt vmcnt(8)
	s_waitcnt lgkmcnt(0)
	s_barrier
	s_waitcnt lgkmcnt(0)
	v_mfma_f32_16x16x32_bf16 v[62:65], v[66:69], v[162:165], v[62:65]
	v_mfma_f32_16x16x32_bf16 v[54:57], v[86:89], v[162:165], v[54:57]
	v_mfma_f32_16x16x32_bf16 v[46:49], v[66:69], v[170:173], v[46:49]
	v_mfma_f32_16x16x32_bf16 v[42:45], v[86:89], v[170:173], v[42:45]
	v_mfma_f32_16x16x32_bf16 v[30:33], v[66:69], v[196:199], v[30:33]
	v_mfma_f32_16x16x32_bf16 v[26:29], v[86:89], v[196:199], v[26:29]
	v_mfma_f32_16x16x32_bf16 v[14:17], v[66:69], v[204:207], v[14:17]
	v_mfma_f32_16x16x32_bf16 v[10:13], v[86:89], v[204:207], v[10:13]
	v_mfma_f32_16x16x32_bf16 v[62:65], v[70:73], v[166:169], v[62:65]
	v_mfma_f32_16x16x32_bf16 v[54:57], v[106:109], v[166:169], v[54:57]
	v_mfma_f32_16x16x32_bf16 v[46:49], v[70:73], v[174:177], v[46:49]
	v_mfma_f32_16x16x32_bf16 v[42:45], v[106:109], v[174:177], v[42:45]
	v_mfma_f32_16x16x32_bf16 v[30:33], v[70:73], v[200:203], v[30:33]
	v_mfma_f32_16x16x32_bf16 v[26:29], v[106:109], v[200:203], v[26:29]
	v_mfma_f32_16x16x32_bf16 v[14:17], v[70:73], v[208:211], v[14:17]
	v_mfma_f32_16x16x32_bf16 v[10:13], v[106:109], v[208:211], v[10:13]
	v_mfma_f32_16x16x32_bf16 v[58:61], v[146:149], v[162:165], v[58:61]
	v_mfma_f32_16x16x32_bf16 v[50:53], v[154:157], v[162:165], v[50:53]
	v_mfma_f32_16x16x32_bf16 v[38:41], v[146:149], v[170:173], v[38:41]
	v_mfma_f32_16x16x32_bf16 v[34:37], v[154:157], v[170:173], v[34:37]
	v_mfma_f32_16x16x32_bf16 v[22:25], v[146:149], v[196:199], v[22:25]
	v_mfma_f32_16x16x32_bf16 v[18:21], v[154:157], v[196:199], v[18:21]
	v_mfma_f32_16x16x32_bf16 v[6:9], v[146:149], v[204:207], v[6:9]
	v_mfma_f32_16x16x32_bf16 v[2:5], v[154:157], v[204:207], v[2:5]
	v_mfma_f32_16x16x32_bf16 v[58:61], v[150:153], v[166:169], v[58:61]
	v_mfma_f32_16x16x32_bf16 v[50:53], v[158:161], v[166:169], v[50:53]
	v_mfma_f32_16x16x32_bf16 v[38:41], v[150:153], v[174:177], v[38:41]
	v_mfma_f32_16x16x32_bf16 v[34:37], v[158:161], v[174:177], v[34:37]
	v_mfma_f32_16x16x32_bf16 v[22:25], v[150:153], v[200:203], v[22:25]
	v_mfma_f32_16x16x32_bf16 v[18:21], v[158:161], v[200:203], v[18:21]
	v_mfma_f32_16x16x32_bf16 v[6:9], v[150:153], v[208:211], v[6:9]
	v_mfma_f32_16x16x32_bf16 v[2:5], v[158:161], v[208:211], v[2:5]
	s_barrier
	s_add_i32 s22, s22, 2
	s_add_u32 s8, s8, 0x100
	s_addc_u32 s9, s9, 0
	s_add_u32 s5, s5, 0x100
	s_addc_u32 s7, s7, 0
	s_cmp_gt_u32 s22, 13
	s_cbranch_scc0 .LBB0_991
	s_and_b64 vcc, exec, s[30:31]
	s_cbranch_vccz .LBB0_994

.LBB0_1040:
	s_setprio 0
	s_waitcnt vmcnt(0)
	s_barrier
	s_and_saveexec_b64 s[6:7], s[80:81]
	s_cbranch_execz .LBB0_1055
	s_add_i32 s0, 0, 0x20164
	v_mov_b32_e32 v2, s0
	v_readlane_b32 s0, v246, 2
	v_mov_b32_e32 v3, 0x3000
	v_readlane_b32 s1, v246, 3
	ds_read_b32 v2, v2
	s_add_u32 s10, s0, 0x3280
	s_addc_u32 s11, s1, 0
	s_nop 1
	global_load_dword v3, v3, s[0:1] offset:640 sc1
	buffer_inv sc1
	s_waitcnt vmcnt(0) lgkmcnt(0)
	v_cmp_ge_u32_e32 vcc, v3, v2
	s_cbranch_vccnz .LBB0_1055
	v_readlane_b32 s0, v246, 2
	v_readlane_b32 s1, v246, 3
	s_add_u32 s8, s0, 0x4200
	s_addc_u32 s9, s1, 0
	s_mov_b32 s0, 1
	v_mov_b32_e32 v3, 0
	s_branch .LBB0_1044

.LBB0_1100:
	s_or_b64 exec, exec, s[6:7]
	v_readlane_b32 s0, v246, 2
	v_readlane_b32 s1, v246, 3
	s_add_u32 s7, s0, 0xf800000
	v_lshrrev_b32_e32 v1, 5, v0
	v_lshrrev_b32_e32 v3, 1, v0
	s_addc_u32 s18, s1, 0
	v_and_b32_e32 v1, 4, v1
	v_bfe_u32 v2, v0, 2, 2
	v_and_b32_e32 v10, 24, v3
	s_add_u32 s2, s0, 0x1e00000
	v_or3_b32 v1, v1, v2, v10
	v_lshlrev_b32_e32 v2, 4, v0
	v_bfe_u32 v3, v0, 3, 25
	v_and_b32_e32 v5, 32, v0
	s_addc_u32 s3, s1, 0
	v_or_b32_e32 v3, 64, v3
	s_movk_i32 s1, 0x60
	v_bitop3_b32 v11, v2, v5, 48 bitop3:0x6c
	v_and_b32_e32 v12, 64, v0
	v_and_or_b32 v4, v3, s1, v1
	v_or_b32_e32 v2, v11, v12
	v_mul_u32_u24_e32 v4, 0xb00, v4
	v_lshrrev_b32_e32 v2, 1, v2
	v_or_b32_e32 v4, v4, v2
	v_lshlrev_b32_e32 v130, 1, v4
	v_bfe_u32 v4, v0, 2, 4
	s_movk_i32 s1, 0x70
	v_and_or_b32 v3, v3, s1, v4
	v_mul_u32_u24_e32 v13, 0xb00, v3
	v_readfirstlane_b32 s16, v0
	v_or_b32_e32 v3, v13, v2
	s_ashr_i32 s28, s86, 1
	s_and_b32 s47, s86, 3
	s_lshr_b32 s0, s16, 6
	v_lshlrev_b32_e32 v132, 1, v3
	v_lshrrev_b32_e32 v3, 3, v0
	s_and_b32 s48, s28, -2
	s_lshr_b32 s17, s16, 8
	s_lshl_b32 s6, s0, 10
	v_and_or_b32 v1, v3, 32, v1
	s_mul_i32 s4, s47, 0x160000
	v_mul_u32_u24_e32 v1, 0xb00, v1
	s_add_u32 s24, s2, s4
	v_or_b32_e32 v1, v1, v2
	s_addc_u32 s25, s3, 0
	s_add_i32 s4, s6, 0
	v_lshlrev_b32_e32 v134, 1, v1
	s_add_i32 m0, s4, 0x10000
	s_barrier
	global_load_lds_dwordx4 v134, s[24:25]
	s_add_i32 m0, s4, 0x12000
	s_add_u32 s8, s24, 0xb0000
	global_load_lds_dwordx4 v130, s[24:25]
	s_addc_u32 s9, s25, 0
	s_add_i32 m0, s4, 0x14000
	v_and_or_b32 v1, v3, 48, v4
	s_mul_i32 s5, s48, 0x160000
	global_load_lds_dwordx4 v134, s[8:9]
	s_add_i32 m0, s4, 0x16000
	v_mul_u32_u24_e32 v14, 0xb00, v1
	s_mul_hi_i32 s1, s48, 0x160000
	s_add_u32 s22, s7, s5
	v_or_b32_e32 v1, v2, v14
	s_addc_u32 s23, s18, s1
	s_add_i32 s5, s4, 0x2000
	v_lshlrev_b32_e32 v136, 1, v1
	global_load_lds_dwordx4 v130, s[8:9]
	s_mov_b32 m0, s4
	s_add_u32 s8, s22, 0xb0000
	global_load_lds_dwordx4 v136, s[22:23]
	s_mov_b32 m0, s5
	s_addc_u32 s9, s23, 0
	s_add_i32 s29, s4, 0x4000
	global_load_lds_dwordx4 v132, s[22:23]
	s_mov_b32 m0, s29
	s_add_i32 s30, s4, 0x6000
	global_load_lds_dwordx4 v136, s[8:9]
	s_mov_b32 m0, s30
	v_mov_b32_e32 v135, 0
	global_load_lds_dwordx4 v132, s[8:9]
	v_readlane_b32 s8, v246, 0
	v_readlane_b32 s9, v246, 1
	s_load_dwordx2 s[8:9], s[8:9], 0xa0
	v_mov_b32_e32 v131, v135
	v_mov_b32_e32 v137, v135
	v_mov_b32_e32 v133, v135
	s_cmp_eq_u32 s17, 1
	s_mov_b32 s49, 4
	v_lshl_add_u64 v[8:9], s[24:25], 0, v[134:135]
	v_lshl_add_u64 v[6:7], s[24:25], 0, v[130:131]
	v_lshl_add_u64 v[2:3], s[22:23], 0, v[136:137]
	s_cselect_b64 s[10:11], -1, 0
	s_cmp_lg_u32 s17, 1
	v_lshl_add_u64 v[4:5], s[22:23], 0, v[132:133]
	s_cbranch_scc1 .LBB0_1102
	s_barrier
	s_setprio 1

.LBB0_1108:
	ds_read_b128 v[142:145], v150
	ds_read_b128 v[156:159], v150 offset:1024
	ds_read_b128 v[160:163], v150 offset:2048
	ds_read_b128 v[164:167], v150 offset:3072
	ds_read_b128 v[168:171], v151
	ds_read_b128 v[172:175], v151 offset:1024
	ds_read_b128 v[180:183], v151 offset:2048
	ds_read_b128 v[184:187], v151 offset:3072
	s_add_u32 s24, s22, 0xfff50080
	s_addc_u32 s25, s23, -1
	s_cmp_eq_u32 s51, 40
	s_cselect_b32 s27, s21, s25
	s_cselect_b32 s26, s20, s24
	s_cselect_b32 s25, s19, s50
	s_cselect_b32 s24, s18, s49
	s_mov_b32 m0, s36
	ds_read_b128 v[188:191], v152
	ds_read_b128 v[192:195], v152 offset:1024
	ds_read_b128 v[196:199], v152 offset:2048
	ds_read_b128 v[200:203], v152 offset:3072
	ds_read_b128 v[204:207], v152 offset:4096
	ds_read_b128 v[208:211], v152 offset:5120
	ds_read_b128 v[212:215], v152 offset:6144
	ds_read_b128 v[216:219], v152 offset:7168
	global_load_lds_dwordx4 v138, s[22:23]
	s_mov_b32 m0, s37
	s_nop 0
	global_load_lds_dwordx4 v140, s[22:23]
	s_waitcnt vmcnt(8)
	s_waitcnt lgkmcnt(0)
	s_barrier
	s_waitcnt lgkmcnt(0)
	v_mfma_f32_16x16x32_bf16 v[126:129], v[142:145], v[188:191], v[126:129]
	v_mfma_f32_16x16x32_bf16 v[122:125], v[160:163], v[188:191], v[122:125]
	v_mfma_f32_16x16x32_bf16 v[110:113], v[142:145], v[196:199], v[110:113]
	v_mfma_f32_16x16x32_bf16 v[106:109], v[160:163], v[196:199], v[106:109]
	v_mfma_f32_16x16x32_bf16 v[94:97], v[142:145], v[204:207], v[94:97]
	v_mfma_f32_16x16x32_bf16 v[90:93], v[160:163], v[204:207], v[90:93]
	v_mfma_f32_16x16x32_bf16 v[78:81], v[142:145], v[212:215], v[78:81]
	v_mfma_f32_16x16x32_bf16 v[74:77], v[160:163], v[212:215], v[74:77]
	v_mfma_f32_16x16x32_bf16 v[126:129], v[156:159], v[192:195], v[126:129]
	v_mfma_f32_16x16x32_bf16 v[122:125], v[164:167], v[192:195], v[122:125]
	v_mfma_f32_16x16x32_bf16 v[110:113], v[156:159], v[200:203], v[110:113]
	v_mfma_f32_16x16x32_bf16 v[106:109], v[164:167], v[200:203], v[106:109]
	v_mfma_f32_16x16x32_bf16 v[94:97], v[156:159], v[208:211], v[94:97]
	v_mfma_f32_16x16x32_bf16 v[90:93], v[164:167], v[208:211], v[90:93]
	v_mfma_f32_16x16x32_bf16 v[78:81], v[156:159], v[216:219], v[78:81]
	v_mfma_f32_16x16x32_bf16 v[74:77], v[164:167], v[216:219], v[74:77]
	v_mfma_f32_16x16x32_bf16 v[118:121], v[168:171], v[188:191], v[118:121]
	v_mfma_f32_16x16x32_bf16 v[114:117], v[180:183], v[188:191], v[114:117]
	v_mfma_f32_16x16x32_bf16 v[102:105], v[168:171], v[196:199], v[102:105]
	v_mfma_f32_16x16x32_bf16 v[98:101], v[180:183], v[196:199], v[98:101]
	v_mfma_f32_16x16x32_bf16 v[86:89], v[168:171], v[204:207], v[86:89]
	v_mfma_f32_16x16x32_bf16 v[82:85], v[180:183], v[204:207], v[82:85]
	v_mfma_f32_16x16x32_bf16 v[70:73], v[168:171], v[212:215], v[70:73]
	v_mfma_f32_16x16x32_bf16 v[66:69], v[180:183], v[212:215], v[66:69]
	v_mfma_f32_16x16x32_bf16 v[118:121], v[172:175], v[192:195], v[118:121]
	v_mfma_f32_16x16x32_bf16 v[114:117], v[184:187], v[192:195], v[114:117]
	v_mfma_f32_16x16x32_bf16 v[102:105], v[172:175], v[200:203], v[102:105]
	v_mfma_f32_16x16x32_bf16 v[98:101], v[184:187], v[200:203], v[98:101]
	v_mfma_f32_16x16x32_bf16 v[86:89], v[172:175], v[208:211], v[86:89]
	v_mfma_f32_16x16x32_bf16 v[82:85], v[184:187], v[208:211], v[82:85]
	v_mfma_f32_16x16x32_bf16 v[70:73], v[172:175], v[216:219], v[70:73]
	v_mfma_f32_16x16x32_bf16 v[66:69], v[184:187], v[216:219], v[66:69]
	s_barrier
	s_mov_b32 m0, s38
	s_add_u32 s52, s24, 0xb0000
	ds_read_b128 v[188:191], v152 offset:16384
	ds_read_b128 v[192:195], v152 offset:17408
	ds_read_b128 v[196:199], v152 offset:18432
	ds_read_b128 v[200:203], v152 offset:19456
	ds_read_b128 v[204:207], v152 offset:20480
	ds_read_b128 v[208:211], v152 offset:21504
	ds_read_b128 v[212:215], v152 offset:22528
	ds_read_b128 v[216:219], v152 offset:23552
	global_load_lds_dwordx4 v134, s[24:25]
	s_mov_b32 m0, s39
	s_addc_u32 s53, s25, 0
	global_load_lds_dwordx4 v130, s[24:25]
	s_mov_b32 m0, s40
	s_nop 0
	global_load_lds_dwordx4 v134, s[52:53]
	s_mov_b32 m0, s41
	s_nop 0
	global_load_lds_dwordx4 v130, s[52:53]
	s_mov_b32 m0, s4
	s_nop 0
	global_load_lds_dwordx4 v136, s[26:27]
	s_mov_b32 m0, s5
	s_nop 0
	global_load_lds_dwordx4 v132, s[26:27]
	s_waitcnt vmcnt(8)
	s_waitcnt lgkmcnt(0)
	s_barrier
	s_waitcnt lgkmcnt(0)
	v_mfma_f32_16x16x32_bf16 v[62:65], v[142:145], v[188:191], v[62:65]
	v_mfma_f32_16x16x32_bf16 v[58:61], v[160:163], v[188:191], v[58:61]
	v_mfma_f32_16x16x32_bf16 v[46:49], v[142:145], v[196:199], v[46:49]
	v_mfma_f32_16x16x32_bf16 v[42:45], v[160:163], v[196:199], v[42:45]
	v_mfma_f32_16x16x32_bf16 v[34:37], v[142:145], v[204:207], v[34:37]
	v_mfma_f32_16x16x32_bf16 v[26:29], v[160:163], v[204:207], v[26:29]
	v_mfma_f32_16x16x32_bf16 v[18:21], v[142:145], v[212:215], v[18:21]
	v_mfma_f32_16x16x32_bf16 v[10:13], v[160:163], v[212:215], v[10:13]
	v_mfma_f32_16x16x32_bf16 v[62:65], v[156:159], v[192:195], v[62:65]
	v_mfma_f32_16x16x32_bf16 v[58:61], v[164:167], v[192:195], v[58:61]
	v_mfma_f32_16x16x32_bf16 v[46:49], v[156:159], v[200:203], v[46:49]
	v_mfma_f32_16x16x32_bf16 v[42:45], v[164:167], v[200:203], v[42:45]
	v_mfma_f32_16x16x32_bf16 v[34:37], v[156:159], v[208:211], v[34:37]
	v_mfma_f32_16x16x32_bf16 v[26:29], v[164:167], v[208:211], v[26:29]
	v_mfma_f32_16x16x32_bf16 v[18:21], v[156:159], v[216:219], v[18:21]
	v_mfma_f32_16x16x32_bf16 v[10:13], v[164:167], v[216:219], v[10:13]
	v_mfma_f32_16x16x32_bf16 v[54:57], v[168:171], v[188:191], v[54:57]
	v_mfma_f32_16x16x32_bf16 v[50:53], v[180:183], v[188:191], v[50:53]
	v_mfma_f32_16x16x32_bf16 v[38:41], v[168:171], v[196:199], v[38:41]
	v_mfma_f32_16x16x32_bf16 v[30:33], v[180:183], v[196:199], v[30:33]
	v_mfma_f32_16x16x32_bf16 v[22:25], v[168:171], v[204:207], v[22:25]
	v_mfma_f32_16x16x32_bf16 v[14:17], v[180:183], v[204:207], v[14:17]
	v_mfma_f32_16x16x32_bf16 v[6:9], v[168:171], v[212:215], v[6:9]
	v_mfma_f32_16x16x32_bf16 v[2:5], v[180:183], v[212:215], v[2:5]
	v_mfma_f32_16x16x32_bf16 v[54:57], v[172:175], v[192:195], v[54:57]
	v_mfma_f32_16x16x32_bf16 v[50:53], v[184:187], v[192:195], v[50:53]
	v_mfma_f32_16x16x32_bf16 v[38:41], v[172:175], v[200:203], v[38:41]
	v_mfma_f32_16x16x32_bf16 v[30:33], v[184:187], v[200:203], v[30:33]
	v_mfma_f32_16x16x32_bf16 v[22:25], v[172:175], v[208:211], v[22:25]
	v_mfma_f32_16x16x32_bf16 v[14:17], v[184:187], v[208:211], v[14:17]
	v_mfma_f32_16x16x32_bf16 v[6:9], v[172:175], v[216:219], v[6:9]
	v_mfma_f32_16x16x32_bf16 v[2:5], v[184:187], v[216:219], v[2:5]
	s_barrier
	ds_read_b128 v[142:145], v153
	ds_read_b128 v[156:159], v153 offset:1024
	ds_read_b128 v[160:163], v153 offset:2048
	ds_read_b128 v[164:167], v153 offset:3072
	ds_read_b128 v[168:171], v154
	ds_read_b128 v[172:175], v154 offset:1024
	ds_read_b128 v[180:183], v154 offset:2048
	ds_read_b128 v[184:187], v154 offset:3072
	s_add_u32 s26, s26, 0xb0000
	s_addc_u32 s27, s27, 0
	s_mov_b32 m0, s29
	ds_read_b128 v[188:191], v152 offset:32768
	ds_read_b128 v[192:195], v152 offset:33792
	ds_read_b128 v[196:199], v152 offset:34816
	ds_read_b128 v[200:203], v152 offset:35840
	ds_read_b128 v[204:207], v152 offset:36864
	ds_read_b128 v[208:211], v152 offset:37888
	ds_read_b128 v[212:215], v152 offset:38912
	ds_read_b128 v[216:219], v152 offset:39936
	global_load_lds_dwordx4 v136, s[26:27]
	s_mov_b32 m0, s30
	s_nop 0
	global_load_lds_dwordx4 v132, s[26:27]
	s_waitcnt vmcnt(8)
	s_waitcnt lgkmcnt(0)
	s_barrier
	s_waitcnt lgkmcnt(0)
	v_mfma_f32_16x16x32_bf16 v[126:129], v[142:145], v[188:191], v[126:129]
	v_mfma_f32_16x16x32_bf16 v[122:125], v[160:163], v[188:191], v[122:125]
	v_mfma_f32_16x16x32_bf16 v[110:113], v[142:145], v[196:199], v[110:113]
	v_mfma_f32_16x16x32_bf16 v[106:109], v[160:163], v[196:199], v[106:109]
	v_mfma_f32_16x16x32_bf16 v[94:97], v[142:145], v[204:207], v[94:97]
	v_mfma_f32_16x16x32_bf16 v[90:93], v[160:163], v[204:207], v[90:93]
	v_mfma_f32_16x16x32_bf16 v[78:81], v[142:145], v[212:215], v[78:81]
	v_mfma_f32_16x16x32_bf16 v[74:77], v[160:163], v[212:215], v[74:77]
	v_mfma_f32_16x16x32_bf16 v[126:129], v[156:159], v[192:195], v[126:129]
	v_mfma_f32_16x16x32_bf16 v[122:125], v[164:167], v[192:195], v[122:125]
	v_mfma_f32_16x16x32_bf16 v[110:113], v[156:159], v[200:203], v[110:113]
	v_mfma_f32_16x16x32_bf16 v[106:109], v[164:167], v[200:203], v[106:109]
	v_mfma_f32_16x16x32_bf16 v[94:97], v[156:159], v[208:211], v[94:97]
	v_mfma_f32_16x16x32_bf16 v[90:93], v[164:167], v[208:211], v[90:93]
	v_mfma_f32_16x16x32_bf16 v[78:81], v[156:159], v[216:219], v[78:81]
	v_mfma_f32_16x16x32_bf16 v[74:77], v[164:167], v[216:219], v[74:77]
	v_mfma_f32_16x16x32_bf16 v[118:121], v[168:171], v[188:191], v[118:121]
	v_mfma_f32_16x16x32_bf16 v[114:117], v[180:183], v[188:191], v[114:117]
	v_mfma_f32_16x16x32_bf16 v[102:105], v[168:171], v[196:199], v[102:105]
	v_mfma_f32_16x16x32_bf16 v[98:101], v[180:183], v[196:199], v[98:101]
	v_mfma_f32_16x16x32_bf16 v[86:89], v[168:171], v[204:207], v[86:89]
	v_mfma_f32_16x16x32_bf16 v[82:85], v[180:183], v[204:207], v[82:85]
	v_mfma_f32_16x16x32_bf16 v[70:73], v[168:171], v[212:215], v[70:73]
	v_mfma_f32_16x16x32_bf16 v[66:69], v[180:183], v[212:215], v[66:69]
	v_mfma_f32_16x16x32_bf16 v[118:121], v[172:175], v[192:195], v[118:121]
	v_mfma_f32_16x16x32_bf16 v[114:117], v[184:187], v[192:195], v[114:117]
	v_mfma_f32_16x16x32_bf16 v[102:105], v[172:175], v[200:203], v[102:105]
	v_mfma_f32_16x16x32_bf16 v[98:101], v[184:187], v[200:203], v[98:101]
	v_mfma_f32_16x16x32_bf16 v[86:89], v[172:175], v[208:211], v[86:89]
	v_mfma_f32_16x16x32_bf16 v[82:85], v[184:187], v[208:211], v[82:85]
	v_mfma_f32_16x16x32_bf16 v[70:73], v[172:175], v[216:219], v[70:73]
	v_mfma_f32_16x16x32_bf16 v[66:69], v[184:187], v[216:219], v[66:69]
	s_barrier
	s_mov_b32 m0, s42
	ds_read_b128 v[188:191], v152 offset:49152
	ds_read_b128 v[192:195], v152 offset:50176
	ds_read_b128 v[196:199], v152 offset:51200
	ds_read_b128 v[200:203], v152 offset:52224
	ds_read_b128 v[204:207], v152 offset:53248
	ds_read_b128 v[208:211], v152 offset:54272
	ds_read_b128 v[212:215], v152 offset:55296
	ds_read_b128 v[216:219], v152 offset:56320
	s_add_u32 s98, s24, 0x80
	s_addc_u32 s99, s25, 0
	global_load_lds_dwordx4 v134, s[98:99]
	s_mov_b32 m0, s43
	s_add_u32 s24, s24, 0xb0080
	s_addc_u32 s25, s25, 0
	global_load_lds_dwordx4 v130, s[98:99]
	s_mov_b32 m0, s44
	s_nop 0
	global_load_lds_dwordx4 v134, s[24:25]
	s_mov_b32 m0, s45
	s_nop 0
	global_load_lds_dwordx4 v130, s[24:25]
	s_add_u32 s98, s26, 0xfff50080
	s_addc_u32 s99, s27, -1
	s_mov_b32 m0, s0
	s_nop 0
	global_load_lds_dwordx4 v136, s[98:99]
	s_mov_b32 m0, s1
	s_nop 0
	global_load_lds_dwordx4 v132, s[98:99]
	s_waitcnt vmcnt(8)
	s_waitcnt lgkmcnt(0)
	s_barrier
	s_waitcnt lgkmcnt(0)
	v_mfma_f32_16x16x32_bf16 v[62:65], v[142:145], v[188:191], v[62:65]
	v_mfma_f32_16x16x32_bf16 v[58:61], v[160:163], v[188:191], v[58:61]
	v_mfma_f32_16x16x32_bf16 v[46:49], v[142:145], v[196:199], v[46:49]
	v_mfma_f32_16x16x32_bf16 v[42:45], v[160:163], v[196:199], v[42:45]
	v_mfma_f32_16x16x32_bf16 v[34:37], v[142:145], v[204:207], v[34:37]
	v_mfma_f32_16x16x32_bf16 v[26:29], v[160:163], v[204:207], v[26:29]
	v_mfma_f32_16x16x32_bf16 v[18:21], v[142:145], v[212:215], v[18:21]
	v_mfma_f32_16x16x32_bf16 v[10:13], v[160:163], v[212:215], v[10:13]
	v_mfma_f32_16x16x32_bf16 v[62:65], v[156:159], v[192:195], v[62:65]
	v_mfma_f32_16x16x32_bf16 v[58:61], v[164:167], v[192:195], v[58:61]
	v_mfma_f32_16x16x32_bf16 v[46:49], v[156:159], v[200:203], v[46:49]
	v_mfma_f32_16x16x32_bf16 v[42:45], v[164:167], v[200:203], v[42:45]
	v_mfma_f32_16x16x32_bf16 v[34:37], v[156:159], v[208:211], v[34:37]
	v_mfma_f32_16x16x32_bf16 v[26:29], v[164:167], v[208:211], v[26:29]
	v_mfma_f32_16x16x32_bf16 v[18:21], v[156:159], v[216:219], v[18:21]
	v_mfma_f32_16x16x32_bf16 v[10:13], v[164:167], v[216:219], v[10:13]
	v_mfma_f32_16x16x32_bf16 v[54:57], v[168:171], v[188:191], v[54:57]
	v_mfma_f32_16x16x32_bf16 v[50:53], v[180:183], v[188:191], v[50:53]
	v_mfma_f32_16x16x32_bf16 v[38:41], v[168:171], v[196:199], v[38:41]
	v_mfma_f32_16x16x32_bf16 v[30:33], v[180:183], v[196:199], v[30:33]
	v_mfma_f32_16x16x32_bf16 v[22:25], v[168:171], v[204:207], v[22:25]
	v_mfma_f32_16x16x32_bf16 v[14:17], v[180:183], v[204:207], v[14:17]
	v_mfma_f32_16x16x32_bf16 v[6:9], v[168:171], v[212:215], v[6:9]
	v_mfma_f32_16x16x32_bf16 v[2:5], v[180:183], v[212:215], v[2:5]
	v_mfma_f32_16x16x32_bf16 v[54:57], v[172:175], v[192:195], v[54:57]
	v_mfma_f32_16x16x32_bf16 v[50:53], v[184:187], v[192:195], v[50:53]
	v_mfma_f32_16x16x32_bf16 v[38:41], v[172:175], v[200:203], v[38:41]
	v_mfma_f32_16x16x32_bf16 v[30:33], v[184:187], v[200:203], v[30:33]
	v_mfma_f32_16x16x32_bf16 v[22:25], v[172:175], v[208:211], v[22:25]
	v_mfma_f32_16x16x32_bf16 v[14:17], v[184:187], v[208:211], v[14:17]
	v_mfma_f32_16x16x32_bf16 v[6:9], v[172:175], v[216:219], v[6:9]
	v_mfma_f32_16x16x32_bf16 v[2:5], v[184:187], v[216:219], v[2:5]
	s_barrier
	s_add_i32 s51, s51, 2
	s_add_u32 s22, s22, 0x100
	s_addc_u32 s23, s23, 0
	s_add_u32 s49, s49, 0x100
	s_addc_u32 s50, s50, 0
	s_cmp_gt_u32 s51, 41
	s_cbranch_scc0 .LBB0_1108
	s_and_b64 vcc, exec, s[16:17]
	s_cbranch_vccz .LBB0_1111
	s_barrier

.LBB0_1114:
	s_setprio 0
	s_waitcnt vmcnt(0)
	s_barrier
	s_and_saveexec_b64 s[6:7], s[80:81]
	s_cbranch_execz .LBB0_1129
	v_readlane_b32 s98, v246, 2
	v_readlane_b32 s99, v246, 3
	s_add_u32 s98, s98, 0x3e40
	s_addc_u32 s99, s99, 0
	v_mov_b32_e32 v248, 0
	v_mov_b32_e32 v247, 1
	s_mov_b32 s100, 1
	global_atomic_add v247, v248, v247, s[98:99] sc0
	s_add_i32 s0, 0, 0x20164
	v_mov_b32_e32 v2, s0
	v_readlane_b32 s0, v246, 2
	v_mov_b32_e32 v3, 0x3000
	v_readlane_b32 s1, v246, 3
	ds_read_b32 v2, v2
	s_add_u32 s10, s0, 0x32c0
	s_addc_u32 s11, s1, 0
	s_nop 1
	global_load_dword v3, v3, s[0:1] offset:704 sc1
	buffer_inv sc1
	s_waitcnt vmcnt(0) lgkmcnt(0)
	v_cmp_ge_u32_e32 vcc, v3, v2
	s_cbranch_vccnz .LBB0_1129
	v_readlane_b32 s0, v246, 2
	v_readlane_b32 s1, v246, 3
	s_add_u32 s8, s0, 0x4200
	s_addc_u32 s9, s1, 0
	s_mov_b32 s0, 1
	v_mov_b32_e32 v3, 0
	s_branch .LBB0_1118
